# retout epilogue: 16-lane row sums via DPP adds (quad_perm / row_half_mirror / row_mirror) instead of ds_bpermute round trips
# speedup vs baseline: 1.1553x; 1.0017x over previous
.LBB0_120:
	v_lshrrev_b32_e32 v11, 3, v52
	v_lshrrev_b32_e32 v12, 1, v53
	v_bfe_u32 v13, v53, 1, 3
	v_bitop3_b32 v12, v11, v12, 7 bitop3:0x78
	v_lshlrev_b32_e32 v14, 1, v50
	v_lshl_or_b32 v12, v12, 4, v14
	v_bitop3_b32 v11, v11, v13, 1 bitop3:0x36
	v_cvt_pk_bf16_f32 v2, v84, v85
	v_cvt_pk_bf16_f32 v3, v82, v83
	v_cvt_pk_bf16_f32 v4, v80, v81
	v_cvt_pk_bf16_f32 v5, v78, v79
	v_add_u32_e32 v12, 0, v12
	v_lshl_or_b32 v11, v11, 4, v14
	v_lshrrev_b32_e32 v10, 4, v133
	s_ashr_i32 s1, s3, 6
	v_cvt_pk_bf16_f32 v6, v74, v75
	v_cvt_pk_bf16_f32 v7, v72, v73
	v_cvt_pk_bf16_f32 v8, v70, v71
	v_cvt_pk_bf16_f32 v9, v68, v69
	ds_write_b128 v12, v[2:5] offset:49152
	ds_write_b128 v12, v[6:9] offset:57344
	v_cvt_pk_bf16_f32 v2, v76, v77
	v_cvt_pk_bf16_f32 v3, v66, v67
	v_cvt_pk_bf16_f32 v4, v64, v65
	v_cvt_pk_bf16_f32 v5, v54, v55
	v_add_u32_e32 v11, 0, v11
	v_bfe_u32 v78, v133, 1, 3
	v_and_b32_e32 v0, 15, v133
	v_cvt_pk_bf16_f32 v6, v62, v63
	v_cvt_pk_bf16_f32 v7, v60, v61
	v_cvt_pk_bf16_f32 v8, v58, v59
	v_cvt_pk_bf16_f32 v9, v56, v57
	ds_write_b128 v11, v[2:5] offset:49152
	ds_write_b128 v11, v[6:9] offset:57344
	v_bitop3_b32 v2, v10, v78, 3 bitop3:0x6c
	s_lshl_b32 s0, s1, 12
	s_add_i32 s3, s0, 0
	v_lshlrev_b32_e32 v134, 7, v0
	v_lshlrev_b32_e32 v135, 4, v2
	v_add_u32_e32 v79, s3, v134
	v_or_b32_e32 v10, v135, v134
	v_add_u32_e32 v6, v79, v135
	v_add_u32_e32 v80, 0, v10
	s_waitcnt lgkmcnt(0)
	s_barrier
	ds_read_b128 v[2:5], v6
	ds_read_b128 v[6:9], v6 offset:2048
	ds_read_b128 v[10:13], v80 offset:16384
	ds_read_b128 v[18:21], v80 offset:18432
	ds_read_b128 v[26:29], v80 offset:20480
	ds_read_b128 v[34:37], v80 offset:22528
	ds_read_b128 v[42:45], v80 offset:24576
	ds_read_b128 v[50:53], v80 offset:26624
	ds_read_b128 v[58:61], v80 offset:28672
	ds_read_b128 v[66:69], v80 offset:30720
	ds_read_b128 v[70:73], v80 offset:49152
	ds_read_b128 v[74:77], v80 offset:57344
	s_waitcnt lgkmcnt(1)
	v_mfma_f32_16x16x32_bf16 v[138:141], v[2:5], v[70:73], 0
	v_bfe_u32 v132, v133, 4, 2
	v_lshlrev_b32_e32 v133, 1, v133
	s_movk_i32 s3, 0x1200
	s_waitcnt lgkmcnt(0)
	v_mfma_f32_16x16x32_bf16 v[142:145], v[2:5], v[74:77], 0
	s_mov_b64 s[10:11], 0x1000
	s_movk_i32 s7, 0x1000
	s_mov_b32 s12, 0x3c800000
	v_mfma_f32_16x16x32_bf16 v[146:149], v[6:9], v[70:73], 0
	s_mov_b32 s8, 0x800000
	s_mov_b64 s[34:35], -1
	v_mfma_f32_16x16x32_bf16 v[150:153], v[6:9], v[74:77], 0
	ds_read_b128 v[70:73], v80 offset:51200
	ds_read_b128 v[74:77], v80 offset:59392
	s_waitcnt lgkmcnt(1)
	v_mfma_f32_16x16x32_bf16 v[154:157], v[2:5], v[70:73], 0
	s_waitcnt lgkmcnt(0)
	v_mfma_f32_16x16x32_bf16 v[158:161], v[2:5], v[74:77], 0
	v_mfma_f32_16x16x32_bf16 v[162:165], v[6:9], v[70:73], 0
	v_mfma_f32_16x16x32_bf16 v[166:169], v[6:9], v[74:77], 0
	ds_read_b128 v[70:73], v80 offset:53248
	ds_read_b128 v[74:77], v80 offset:61440
	s_waitcnt lgkmcnt(1)
	v_mfma_f32_16x16x32_bf16 v[170:173], v[2:5], v[70:73], 0
	s_waitcnt lgkmcnt(0)
	v_mfma_f32_16x16x32_bf16 v[176:179], v[2:5], v[74:77], 0
	v_mfma_f32_16x16x32_bf16 v[180:183], v[6:9], v[70:73], 0
	v_mfma_f32_16x16x32_bf16 v[184:187], v[6:9], v[74:77], 0
	ds_read_b128 v[70:73], v80 offset:55296
	ds_read_b128 v[74:77], v80 offset:63488
	v_mfma_f32_16x16x32_bf16 v[14:17], v[2:5], v[10:13], 0
	v_mfma_f32_16x16x32_bf16 v[22:25], v[2:5], v[18:21], 0
	v_mfma_f32_16x16x32_bf16 v[30:33], v[2:5], v[26:29], 0
	v_mfma_f32_16x16x32_bf16 v[38:41], v[2:5], v[34:37], 0
	v_mfma_f32_16x16x32_bf16 v[46:49], v[2:5], v[42:45], 0
	v_mfma_f32_16x16x32_bf16 v[54:57], v[2:5], v[50:53], 0
	v_mfma_f32_16x16x32_bf16 v[62:65], v[2:5], v[58:61], 0
	v_mfma_f32_16x16x32_bf16 v[98:101], v[2:5], v[66:69], 0
	s_waitcnt lgkmcnt(1)
	v_mfma_f32_16x16x32_bf16 v[188:191], v[2:5], v[70:73], 0
	s_waitcnt lgkmcnt(0)
	v_mfma_f32_16x16x32_bf16 v[192:195], v[2:5], v[74:77], 0
	v_bitop3_b32 v2, v132, v78, 4 bitop3:0x36
	v_lshlrev_b32_e32 v136, 4, v2
	v_add_u32_e32 v2, v79, v136
	ds_read_b128 v[208:211], v2
	ds_read_b128 v[212:215], v2 offset:2048
	v_or_b32_e32 v2, v136, v134
	v_add_u32_e32 v137, 0, v2
	ds_read_b128 v[2:5], v137 offset:16384
	v_mfma_f32_16x16x32_bf16 v[10:13], v[6:9], v[10:13], 0
	v_lshlrev_b32_e32 v132, 2, v132
	v_lshl_or_b32 v132, s1, 5, v132
	v_and_b32_e32 v232, 15, v207
	v_lshlrev_b32_e32 v232, 1, v232
	v_mov_b32_e32 v233, 0
	v_mov_b32_e32 v247, 0
	v_or_b32_e32 v246, 0, v132
	v_add_u32_e32 v246, s6, v246
	v_mul_u32_u24_e32 v246, 0x1200, v246
	v_lshl_add_u64 v[248:249], s[92:93], 0, v[246:247]
	v_lshl_add_u64 v[248:249], v[248:249], 0, s[26:27]
	v_lshl_add_u64 v[248:249], v[248:249], 0, v[232:233]
	v_lshl_add_u64 v[248:249], v[248:249], 0, s[10:11]
	global_load_ushort v216, v[248:249], off
	global_load_ushort v217, v[248:249], off offset:32
	global_load_ushort v218, v[248:249], off offset:64
	global_load_ushort v219, v[248:249], off offset:96
	v_or_b32_e32 v246, 1, v132
	v_add_u32_e32 v246, s6, v246
	v_mul_u32_u24_e32 v246, 0x1200, v246
	v_lshl_add_u64 v[248:249], s[92:93], 0, v[246:247]
	v_lshl_add_u64 v[248:249], v[248:249], 0, s[26:27]
	v_lshl_add_u64 v[248:249], v[248:249], 0, v[232:233]
	v_lshl_add_u64 v[248:249], v[248:249], 0, s[10:11]
	global_load_ushort v220, v[248:249], off
	global_load_ushort v221, v[248:249], off offset:32
	global_load_ushort v222, v[248:249], off offset:64
	global_load_ushort v223, v[248:249], off offset:96
	v_or_b32_e32 v246, 2, v132
	v_add_u32_e32 v246, s6, v246
	v_mul_u32_u24_e32 v246, 0x1200, v246
	v_lshl_add_u64 v[248:249], s[92:93], 0, v[246:247]
	v_lshl_add_u64 v[248:249], v[248:249], 0, s[26:27]
	v_lshl_add_u64 v[248:249], v[248:249], 0, v[232:233]
	v_lshl_add_u64 v[248:249], v[248:249], 0, s[10:11]
	global_load_ushort v224, v[248:249], off
	global_load_ushort v225, v[248:249], off offset:32
	global_load_ushort v226, v[248:249], off offset:64
	global_load_ushort v227, v[248:249], off offset:96
	v_or_b32_e32 v246, 3, v132
	v_add_u32_e32 v246, s6, v246
	v_mul_u32_u24_e32 v246, 0x1200, v246
	v_lshl_add_u64 v[248:249], s[92:93], 0, v[246:247]
	v_lshl_add_u64 v[248:249], v[248:249], 0, s[26:27]
	v_lshl_add_u64 v[248:249], v[248:249], 0, v[232:233]
	v_lshl_add_u64 v[248:249], v[248:249], 0, s[10:11]
	global_load_ushort v228, v[248:249], off
	global_load_ushort v229, v[248:249], off offset:32
	global_load_ushort v230, v[248:249], off offset:64
	global_load_ushort v231, v[248:249], off offset:96
	s_waitcnt lgkmcnt(0)
	v_mfma_f32_16x16x32_bf16 v[126:129], v[208:211], v[2:5], v[14:17]
	v_mfma_f32_16x16x32_bf16 v[94:97], v[212:215], v[2:5], v[10:13]
	ds_read_b128 v[2:5], v137 offset:18432
	v_mfma_f32_16x16x32_bf16 v[18:21], v[6:9], v[18:21], 0
	s_waitcnt lgkmcnt(0)
	v_mfma_f32_16x16x32_bf16 v[122:125], v[208:211], v[2:5], v[22:25]
	v_mfma_f32_16x16x32_bf16 v[90:93], v[212:215], v[2:5], v[18:21]
	ds_read_b128 v[2:5], v137 offset:20480
	v_mfma_f32_16x16x32_bf16 v[26:29], v[6:9], v[26:29], 0
	s_waitcnt lgkmcnt(0)
	v_mfma_f32_16x16x32_bf16 v[118:121], v[208:211], v[2:5], v[30:33]
	v_mfma_f32_16x16x32_bf16 v[86:89], v[212:215], v[2:5], v[26:29]
	ds_read_b128 v[2:5], v137 offset:22528
	v_mfma_f32_16x16x32_bf16 v[34:37], v[6:9], v[34:37], 0
	s_waitcnt lgkmcnt(0)
	v_mfma_f32_16x16x32_bf16 v[114:117], v[208:211], v[2:5], v[38:41]
	v_mfma_f32_16x16x32_bf16 v[82:85], v[212:215], v[2:5], v[34:37]
	ds_read_b128 v[2:5], v137 offset:24576
	v_mfma_f32_16x16x32_bf16 v[42:45], v[6:9], v[42:45], 0
	s_waitcnt lgkmcnt(0)
	v_mfma_f32_16x16x32_bf16 v[110:113], v[208:211], v[2:5], v[46:49]
	v_mfma_f32_16x16x32_bf16 v[78:81], v[212:215], v[2:5], v[42:45]
	ds_read_b128 v[2:5], v137 offset:26624
	v_mfma_f32_16x16x32_bf16 v[50:53], v[6:9], v[50:53], 0
	v_mfma_f32_16x16x32_bf16 v[200:203], v[6:9], v[74:77], 0
	s_waitcnt lgkmcnt(0)
	v_mfma_f32_16x16x32_bf16 v[106:109], v[208:211], v[2:5], v[54:57]
	v_mfma_f32_16x16x32_bf16 v[74:77], v[212:215], v[2:5], v[50:53]
	ds_read_b128 v[2:5], v137 offset:28672
	v_mfma_f32_16x16x32_bf16 v[58:61], v[6:9], v[58:61], 0
	v_mfma_f32_16x16x32_bf16 v[196:199], v[6:9], v[70:73], 0
	s_waitcnt lgkmcnt(0)
	v_mfma_f32_16x16x32_bf16 v[102:105], v[208:211], v[2:5], v[62:65]
	v_mfma_f32_16x16x32_bf16 v[70:73], v[212:215], v[2:5], v[58:61]
	ds_read_b128 v[2:5], v137 offset:30720
	v_mfma_f32_16x16x32_bf16 v[66:69], v[6:9], v[66:69], 0
	s_waitcnt lgkmcnt(0)
	v_mfma_f32_16x16x32_bf16 v[98:101], v[208:211], v[2:5], v[98:101]
	v_mfma_f32_16x16x32_bf16 v[66:69], v[212:215], v[2:5], v[66:69]
	ds_read_b128 v[2:5], v137 offset:49152
	ds_read_b128 v[6:9], v137 offset:57344
	ds_read_b128 v[10:13], v137 offset:51200
	ds_read_b128 v[14:17], v137 offset:59392
	ds_read_b128 v[18:21], v137 offset:53248
	ds_read_b128 v[22:25], v137 offset:61440
	s_waitcnt lgkmcnt(5)
	v_mfma_f32_16x16x32_bf16 v[34:37], v[208:211], v[2:5], v[138:141]
	ds_read_b128 v[26:29], v137 offset:55296
	s_nop 1
	ds_read_b128 v[138:141], v137 offset:63488
	v_sub_u32_e32 v137, v132, v0
	v_cmp_lt_i32_e32 vcc, -1, v137
	s_waitcnt lgkmcnt(1)
	v_mfma_f32_16x16x32_bf16 v[62:65], v[208:211], v[26:29], v[188:191]
	s_waitcnt lgkmcnt(0)
	s_barrier
	v_mfma_f32_16x16x32_bf16 v[58:61], v[208:211], v[138:141], v[192:195]
	v_mfma_f32_16x16x32_bf16 v[30:33], v[212:215], v[26:29], v[196:199]
	v_mfma_f32_16x16x32_bf16 v[26:29], v[212:215], v[138:141], v[200:203]
	v_cvt_f32_u32_e32 v138, v137
	v_lshlrev_b32_e32 v140, 7, v132
	v_mul_f32_e32 v138, v138, v131
	v_mul_f32_e32 v138, 0xbfb8aa3b, v138
	v_exp_f32_e32 v138, v138
	v_mfma_f32_16x16x32_bf16 v[2:5], v[212:215], v[2:5], v[146:149]
	v_add_f32_e32 v138, 0, v138
	v_cndmask_b32_e32 v139, 0, v138, vcc
	v_cmp_gt_i32_e32 vcc, 1, v137
	v_sub_u32_e32 v137, 0, v137
	v_cvt_f32_u32_e32 v137, v137
	v_mfma_f32_16x16x32_bf16 v[38:41], v[208:211], v[6:9], v[142:145]
	v_mul_f32_e32 v137, v137, v130
	v_mul_f32_e32 v137, 0xbfb8aa3b, v137
	v_exp_f32_e32 v137, v137
	v_mfma_f32_16x16x32_bf16 v[6:9], v[212:215], v[6:9], v[150:153]
	v_add_f32_e32 v137, v137, v139
	v_lshlrev_b32_e32 v139, 2, v132
	v_cndmask_b32_e32 v138, v138, v137, vcc
	v_bitop3_b32 v137, v139, 56, v0 bitop3:0xc8
	v_mul_f32_e32 v126, v138, v126
	v_lshl_add_u32 v141, v137, 1, 0
	v_and_b32_e32 v137, 14, v133
	v_cvt_pk_bf16_f32 v126, v126, s0
	v_add3_u32 v146, v141, v140, v137
	v_or_b32_e32 v133, 1, v132
	ds_write_b16 v146, v126
	v_sub_u32_e32 v126, v133, v0
	v_cvt_f32_u32_e32 v141, v126
	v_cmp_lt_i32_e32 vcc, -1, v126
	v_mul_f32_e32 v90, v138, v90
	v_cvt_pk_bf16_f32 v90, v90, s0
	v_mul_f32_e32 v141, v141, v131
	v_mul_f32_e32 v141, 0xbfb8aa3b, v141
	v_exp_f32_e32 v141, v141
	v_mfma_f32_16x16x32_bf16 v[42:45], v[208:211], v[10:13], v[154:157]
	v_add_f32_e32 v141, 0, v141
	v_cndmask_b32_e32 v142, 0, v141, vcc
	v_cmp_gt_i32_e32 vcc, 1, v126
	v_sub_u32_e32 v126, 0, v126
	v_cvt_f32_u32_e32 v126, v126
	v_mfma_f32_16x16x32_bf16 v[46:49], v[208:211], v[14:17], v[158:161]
	v_mul_f32_e32 v126, v126, v130
	v_mul_f32_e32 v126, 0xbfb8aa3b, v126
	v_exp_f32_e32 v126, v126
	v_mfma_f32_16x16x32_bf16 v[50:53], v[208:211], v[18:21], v[170:173]
	v_add_f32_e32 v126, v126, v142
	v_cndmask_b32_e32 v126, v141, v126, vcc
	v_lshlrev_b32_e32 v141, 2, v133
	v_mul_f32_e32 v126, v126, v127
	v_bitop3_b32 v127, v141, 56, v0 bitop3:0xc8
	v_lshl_add_u32 v127, v127, 1, 0
	v_lshlrev_b32_e32 v142, 7, v133
	v_cvt_pk_bf16_f32 v126, v126, s0
	v_add3_u32 v147, v127, v142, v137
	v_or_b32_e32 v127, 2, v132
	ds_write_b16 v147, v126
	v_sub_u32_e32 v126, v127, v0
	v_cvt_f32_u32_e32 v143, v126
	v_cmp_lt_i32_e32 vcc, -1, v126
	v_mfma_f32_16x16x32_bf16 v[54:57], v[208:211], v[22:25], v[176:179]
	v_mul_f32_e32 v143, v143, v131
	v_mul_f32_e32 v143, 0xbfb8aa3b, v143
	v_exp_f32_e32 v143, v143
	v_mfma_f32_16x16x32_bf16 v[10:13], v[212:215], v[10:13], v[162:165]
	v_add_f32_e32 v143, 0, v143
	v_cndmask_b32_e32 v144, 0, v143, vcc
	v_cmp_gt_i32_e32 vcc, 1, v126
	v_sub_u32_e32 v126, 0, v126
	v_cvt_f32_u32_e32 v126, v126
	v_mfma_f32_16x16x32_bf16 v[14:17], v[212:215], v[14:17], v[166:169]
	v_mul_f32_e32 v126, v126, v130
	v_mul_f32_e32 v126, 0xbfb8aa3b, v126
	v_exp_f32_e32 v126, v126
	v_mfma_f32_16x16x32_bf16 v[18:21], v[212:215], v[18:21], v[180:183]
	v_add_f32_e32 v126, v126, v144
	v_cndmask_b32_e32 v126, v143, v126, vcc
	v_lshlrev_b32_e32 v143, 2, v127
	v_mul_f32_e32 v126, v126, v128
	v_bitop3_b32 v128, v143, 56, v0 bitop3:0x48
	v_lshl_add_u32 v128, v128, 1, 0
	v_lshlrev_b32_e32 v144, 7, v127
	v_cvt_pk_bf16_f32 v126, v126, s0
	v_add3_u32 v148, v128, v144, v137
	ds_write_b16 v148, v126
	v_or_b32_e32 v126, 3, v132
	v_sub_u32_e32 v128, v126, v0
	v_cvt_f32_u32_e32 v145, v128
	v_cmp_lt_i32_e32 vcc, -1, v128
	v_mfma_f32_16x16x32_bf16 v[22:25], v[212:215], v[22:25], v[184:187]
	v_mul_f32_e32 v145, v145, v131
	v_mul_f32_e32 v145, 0xbfb8aa3b, v145
	v_exp_f32_e32 v145, v145
	s_nop 0
	v_add_f32_e32 v145, 0, v145
	v_cndmask_b32_e32 v149, 0, v145, vcc
	v_cmp_gt_i32_e32 vcc, 1, v128
	v_sub_u32_e32 v128, 0, v128
	v_cvt_f32_u32_e32 v128, v128
	v_mul_f32_e32 v128, v128, v130
	v_mul_f32_e32 v128, 0xbfb8aa3b, v128
	v_exp_f32_e32 v128, v128
	s_nop 0
	v_add_f32_e32 v128, v128, v149
	v_cndmask_b32_e32 v128, v145, v128, vcc
	v_mul_f32_e32 v128, v128, v129
	v_lshlrev_b32_e32 v129, 2, v126
	v_bitop3_b32 v145, v129, 56, v0 bitop3:0x48
	v_lshl_add_u32 v149, v145, 1, 0
	v_lshlrev_b32_e32 v145, 7, v126
	v_cvt_pk_bf16_f32 v128, v128, s0
	v_add3_u32 v149, v149, v145, v137
	ds_write_b16 v149, v128
	v_or_b32_e32 v128, 16, v0
	v_sub_u32_e32 v150, v132, v128
	v_cvt_f32_u32_e32 v151, v150
	v_cmp_lt_i32_e32 vcc, -1, v150
	v_mul_f32_e32 v151, v151, v131
	v_mul_f32_e32 v151, 0xbfb8aa3b, v151
	v_exp_f32_e32 v151, v151
	s_nop 0
	v_add_f32_e32 v151, 0, v151
	v_cndmask_b32_e32 v152, 0, v151, vcc
	v_cmp_gt_i32_e32 vcc, 1, v150
	v_sub_u32_e32 v150, 0, v150
	v_cvt_f32_u32_e32 v150, v150
	v_mul_f32_e32 v150, v150, v130
	v_mul_f32_e32 v150, 0xbfb8aa3b, v150
	v_exp_f32_e32 v150, v150
	s_nop 0
	v_add_f32_e32 v150, v150, v152
	v_cndmask_b32_e32 v150, v151, v150, vcc
	v_mul_f32_e32 v122, v150, v122
	v_bitop3_b32 v150, v139, 56, v128 bitop3:0x48
	v_lshl_add_u32 v150, v150, 1, 0
	v_cvt_pk_bf16_f32 v122, v122, s0
	v_add3_u32 v150, v150, v140, v137
	ds_write_b16 v150, v122
	v_sub_u32_e32 v122, v133, v128
	v_cvt_f32_u32_e32 v150, v122
	v_cmp_lt_i32_e32 vcc, -1, v122
	v_mul_f32_e32 v150, v150, v131
	v_mul_f32_e32 v150, 0xbfb8aa3b, v150
	v_exp_f32_e32 v150, v150
	s_nop 0
	v_add_f32_e32 v150, 0, v150
	v_cndmask_b32_e32 v151, 0, v150, vcc
	v_cmp_gt_i32_e32 vcc, 1, v122
	v_sub_u32_e32 v122, 0, v122
	v_cvt_f32_u32_e32 v122, v122
	v_mul_f32_e32 v122, v122, v130
	v_mul_f32_e32 v122, 0xbfb8aa3b, v122
	v_exp_f32_e32 v122, v122
	s_nop 0
	v_add_f32_e32 v122, v122, v151
	v_cndmask_b32_e32 v122, v150, v122, vcc
	v_mul_f32_e32 v122, v122, v123
	v_bitop3_b32 v123, v141, 56, v128 bitop3:0x48
	v_lshl_add_u32 v123, v123, 1, 0
	v_cvt_pk_bf16_f32 v122, v122, s0
	v_add3_u32 v123, v123, v142, v137
	ds_write_b16 v123, v122
	v_sub_u32_e32 v122, v127, v128
	v_cvt_f32_u32_e32 v123, v122
	v_cmp_lt_i32_e32 vcc, -1, v122
	v_mul_f32_e32 v123, v123, v131
	v_mul_f32_e32 v123, 0xbfb8aa3b, v123
	v_exp_f32_e32 v123, v123
	s_nop 0
	v_add_f32_e32 v123, 0, v123
	v_cndmask_b32_e32 v150, 0, v123, vcc
	v_cmp_gt_i32_e32 vcc, 1, v122
	v_sub_u32_e32 v122, 0, v122
	v_cvt_f32_u32_e32 v122, v122
	v_mul_f32_e32 v122, v122, v130
	v_mul_f32_e32 v122, 0xbfb8aa3b, v122
	v_exp_f32_e32 v122, v122
	s_nop 0
	v_add_f32_e32 v122, v122, v150
	v_cndmask_b32_e32 v122, v123, v122, vcc
	v_bitop3_b32 v123, v143, 56, v128 bitop3:0x48
	v_mul_f32_e32 v122, v122, v124
	v_lshl_add_u32 v123, v123, 1, 0
	v_cvt_pk_bf16_f32 v122, v122, s0
	v_add3_u32 v123, v123, v144, v137
	ds_write_b16 v123, v122
	v_sub_u32_e32 v122, v126, v128
	v_cvt_f32_u32_e32 v123, v122
	v_cmp_lt_i32_e32 vcc, -1, v122
	v_mul_f32_e32 v123, v123, v131
	v_mul_f32_e32 v123, 0xbfb8aa3b, v123
	v_exp_f32_e32 v123, v123
	s_nop 0
	v_add_f32_e32 v123, 0, v123
	v_cndmask_b32_e32 v124, 0, v123, vcc
	v_cmp_gt_i32_e32 vcc, 1, v122
	v_sub_u32_e32 v122, 0, v122
	v_cvt_f32_u32_e32 v122, v122
	v_mul_f32_e32 v122, v122, v130
	v_mul_f32_e32 v122, 0xbfb8aa3b, v122
	v_exp_f32_e32 v122, v122
	s_nop 0
	v_add_f32_e32 v122, v122, v124
	v_cndmask_b32_e32 v122, v123, v122, vcc
	v_bitop3_b32 v123, v129, 56, v128 bitop3:0x48
	v_mul_f32_e32 v122, v122, v125
	v_lshl_add_u32 v123, v123, 1, 0
	v_cvt_pk_bf16_f32 v122, v122, s0
	v_add3_u32 v123, v123, v145, v137
	ds_write_b16 v123, v122
	v_or_b32_e32 v122, 32, v0
	v_sub_u32_e32 v123, v132, v122
	v_cvt_f32_u32_e32 v124, v123
	v_cmp_lt_i32_e32 vcc, -1, v123
	v_mul_f32_e32 v124, v124, v131
	v_mul_f32_e32 v124, 0xbfb8aa3b, v124
	v_exp_f32_e32 v124, v124
	s_nop 0
	v_add_f32_e32 v124, 0, v124
	v_cndmask_b32_e32 v125, 0, v124, vcc
	v_cmp_gt_i32_e32 vcc, 1, v123
	v_sub_u32_e32 v123, 0, v123
	v_cvt_f32_u32_e32 v123, v123
	v_mul_f32_e32 v123, v123, v130
	v_mul_f32_e32 v123, 0xbfb8aa3b, v123
	v_exp_f32_e32 v123, v123
	s_nop 0
	v_add_f32_e32 v123, v123, v125
	v_cndmask_b32_e32 v123, v124, v123, vcc
	v_mul_f32_e32 v118, v123, v118
	v_bitop3_b32 v123, v139, 56, v122 bitop3:0x48
	v_lshl_add_u32 v123, v123, 1, 0
	v_cvt_pk_bf16_f32 v118, v118, s0
	v_add3_u32 v123, v123, v140, v137
	ds_write_b16 v123, v118
	v_sub_u32_e32 v118, v133, v122
	v_cvt_f32_u32_e32 v123, v118
	v_cmp_lt_i32_e32 vcc, -1, v118
	v_mul_f32_e32 v123, v123, v131
	v_mul_f32_e32 v123, 0xbfb8aa3b, v123
	v_exp_f32_e32 v123, v123
	s_nop 0
	v_add_f32_e32 v123, 0, v123
	v_cndmask_b32_e32 v124, 0, v123, vcc
	v_cmp_gt_i32_e32 vcc, 1, v118
	v_sub_u32_e32 v118, 0, v118
	v_cvt_f32_u32_e32 v118, v118
	v_mul_f32_e32 v118, v118, v130
	v_mul_f32_e32 v118, 0xbfb8aa3b, v118
	v_exp_f32_e32 v118, v118
	s_nop 0
	v_add_f32_e32 v118, v118, v124
	v_cndmask_b32_e32 v118, v123, v118, vcc
	v_mul_f32_e32 v118, v118, v119
	v_bitop3_b32 v119, v141, 56, v122 bitop3:0x48
	v_lshl_add_u32 v119, v119, 1, 0
	v_cvt_pk_bf16_f32 v118, v118, s0
	v_add3_u32 v119, v119, v142, v137
	ds_write_b16 v119, v118
	v_sub_u32_e32 v118, v127, v122
	v_cvt_f32_u32_e32 v119, v118
	v_cmp_lt_i32_e32 vcc, -1, v118
	v_add3_u32 v124, 0, v136, v134
	v_add_u32_e32 v125, s0, v124
	v_mul_f32_e32 v119, v119, v131
	v_mul_f32_e32 v119, 0xbfb8aa3b, v119
	v_exp_f32_e32 v119, v119
	s_nop 0
	v_add_f32_e32 v119, 0, v119
	v_cndmask_b32_e32 v123, 0, v119, vcc
	v_cmp_gt_i32_e32 vcc, 1, v118
	v_sub_u32_e32 v118, 0, v118
	v_cvt_f32_u32_e32 v118, v118
	v_mul_f32_e32 v118, v118, v130
	v_mul_f32_e32 v118, 0xbfb8aa3b, v118
	v_exp_f32_e32 v118, v118
	s_nop 0
	v_add_f32_e32 v118, v118, v123
	v_cndmask_b32_e32 v118, v119, v118, vcc
	v_bitop3_b32 v119, v143, 56, v122 bitop3:0x48
	v_mul_f32_e32 v118, v118, v120
	v_lshl_add_u32 v119, v119, 1, 0
	v_cvt_pk_bf16_f32 v118, v118, s0
	v_add3_u32 v119, v119, v144, v137
	ds_write_b16 v119, v118
	v_sub_u32_e32 v118, v126, v122
	v_cvt_f32_u32_e32 v119, v118
	v_cmp_lt_i32_e32 vcc, -1, v118
	v_mul_f32_e32 v119, v119, v131
	v_mul_f32_e32 v119, 0xbfb8aa3b, v119
	v_exp_f32_e32 v119, v119
	s_nop 0
	v_add_f32_e32 v119, 0, v119
	v_cndmask_b32_e32 v120, 0, v119, vcc
	v_cmp_gt_i32_e32 vcc, 1, v118
	v_sub_u32_e32 v118, 0, v118
	v_cvt_f32_u32_e32 v118, v118
	v_mul_f32_e32 v118, v118, v130
	v_mul_f32_e32 v118, 0xbfb8aa3b, v118
	v_exp_f32_e32 v118, v118
	s_nop 0
	v_add_f32_e32 v118, v118, v120
	v_cndmask_b32_e32 v118, v119, v118, vcc
	v_bitop3_b32 v119, v129, 56, v122 bitop3:0x48
	v_mul_f32_e32 v118, v118, v121
	v_lshl_add_u32 v119, v119, 1, 0
	v_cvt_pk_bf16_f32 v118, v118, s0
	v_add3_u32 v119, v119, v145, v137
	ds_write_b16 v119, v118
	v_or_b32_e32 v118, 48, v0
	v_sub_u32_e32 v119, v132, v118
	v_cvt_f32_u32_e32 v120, v119
	v_cmp_lt_i32_e32 vcc, -1, v119
	v_mul_f32_e32 v120, v120, v131
	v_mul_f32_e32 v120, 0xbfb8aa3b, v120
	v_exp_f32_e32 v120, v120
	s_nop 0
	v_add_f32_e32 v120, 0, v120
	v_cndmask_b32_e32 v121, 0, v120, vcc
	v_cmp_gt_i32_e32 vcc, 1, v119
	v_sub_u32_e32 v119, 0, v119
	v_cvt_f32_u32_e32 v119, v119
	v_mul_f32_e32 v119, v119, v130
	v_mul_f32_e32 v119, 0xbfb8aa3b, v119
	v_exp_f32_e32 v119, v119
	s_nop 0
	v_add_f32_e32 v119, v119, v121
	v_cndmask_b32_e32 v119, v120, v119, vcc
	v_mul_f32_e32 v114, v119, v114
	v_bitop3_b32 v119, v139, 56, v118 bitop3:0x48
	v_lshl_add_u32 v119, v119, 1, 0
	v_cvt_pk_bf16_f32 v114, v114, s0
	v_add3_u32 v119, v119, v140, v137
	ds_write_b16 v119, v114
	v_sub_u32_e32 v114, v133, v118
	v_cvt_f32_u32_e32 v119, v114
	v_cmp_lt_i32_e32 vcc, -1, v114
	v_mul_f32_e32 v119, v119, v131
	v_mul_f32_e32 v119, 0xbfb8aa3b, v119
	v_exp_f32_e32 v119, v119
	s_nop 0
	v_add_f32_e32 v119, 0, v119
	v_cndmask_b32_e32 v120, 0, v119, vcc
	v_cmp_gt_i32_e32 vcc, 1, v114
	v_sub_u32_e32 v114, 0, v114
	v_cvt_f32_u32_e32 v114, v114
	v_mul_f32_e32 v114, v114, v130
	v_mul_f32_e32 v114, 0xbfb8aa3b, v114
	v_exp_f32_e32 v114, v114
	s_nop 0
	v_add_f32_e32 v114, v114, v120
	v_cndmask_b32_e32 v114, v119, v114, vcc
	v_mul_f32_e32 v114, v114, v115
	v_bitop3_b32 v115, v141, 56, v118 bitop3:0x48
	v_lshl_add_u32 v115, v115, 1, 0
	v_cvt_pk_bf16_f32 v114, v114, s0
	v_add3_u32 v115, v115, v142, v137
	ds_write_b16 v115, v114
	v_sub_u32_e32 v114, v127, v118
	v_cvt_f32_u32_e32 v115, v114
	v_cmp_lt_i32_e32 vcc, -1, v114
	v_mul_f32_e32 v115, v115, v131
	v_mul_f32_e32 v115, 0xbfb8aa3b, v115
	v_exp_f32_e32 v115, v115
	s_nop 0
	v_add_f32_e32 v115, 0, v115
	v_cndmask_b32_e32 v119, 0, v115, vcc
	v_cmp_gt_i32_e32 vcc, 1, v114
	v_sub_u32_e32 v114, 0, v114
	v_cvt_f32_u32_e32 v114, v114
	v_mul_f32_e32 v114, v114, v130
	v_mul_f32_e32 v114, 0xbfb8aa3b, v114
	v_exp_f32_e32 v114, v114
	s_nop 0
	v_add_f32_e32 v114, v114, v119
	v_cndmask_b32_e32 v114, v115, v114, vcc
	v_bitop3_b32 v115, v143, 56, v118 bitop3:0x48
	v_mul_f32_e32 v114, v114, v116
	v_lshl_add_u32 v115, v115, 1, 0
	v_cvt_pk_bf16_f32 v114, v114, s0
	v_add3_u32 v115, v115, v144, v137
	ds_write_b16 v115, v114
	v_sub_u32_e32 v114, v126, v118
	v_cvt_f32_u32_e32 v115, v114
	v_cmp_lt_i32_e32 vcc, -1, v114
	v_mul_f32_e32 v115, v115, v131
	v_mul_f32_e32 v115, 0xbfb8aa3b, v115
	v_exp_f32_e32 v115, v115
	s_nop 0
	v_add_f32_e32 v115, 0, v115
	v_cndmask_b32_e32 v116, 0, v115, vcc
	v_cmp_gt_i32_e32 vcc, 1, v114
	v_sub_u32_e32 v114, 0, v114
	v_cvt_f32_u32_e32 v114, v114
	v_mul_f32_e32 v114, v114, v130
	v_mul_f32_e32 v114, 0xbfb8aa3b, v114
	v_exp_f32_e32 v114, v114
	s_nop 0
	v_add_f32_e32 v114, v114, v116
	v_cndmask_b32_e32 v114, v115, v114, vcc
	v_bitop3_b32 v115, v129, 56, v118 bitop3:0x48
	v_mul_f32_e32 v114, v114, v117
	v_lshl_add_u32 v115, v115, 1, 0
	v_cvt_pk_bf16_f32 v114, v114, s0
	v_add3_u32 v115, v115, v145, v137
	ds_write_b16 v115, v114
	v_or_b32_e32 v114, 64, v0
	v_sub_u32_e32 v115, v132, v114
	v_cvt_f32_u32_e32 v116, v115
	v_cmp_lt_i32_e32 vcc, -1, v115
	v_mul_f32_e32 v116, v116, v131
	v_mul_f32_e32 v116, 0xbfb8aa3b, v116
	v_exp_f32_e32 v116, v116
	s_nop 0
	v_add_f32_e32 v116, 0, v116
	v_cndmask_b32_e32 v117, 0, v116, vcc
	v_cmp_gt_i32_e32 vcc, 1, v115
	v_sub_u32_e32 v115, 0, v115
	v_cvt_f32_u32_e32 v115, v115
	v_mul_f32_e32 v115, v115, v130
	v_mul_f32_e32 v115, 0xbfb8aa3b, v115
	v_exp_f32_e32 v115, v115
	s_nop 0
	v_add_f32_e32 v115, v115, v117
	v_cndmask_b32_e32 v115, v116, v115, vcc
	v_mul_f32_e32 v110, v115, v110
	v_cvt_pk_bf16_f32 v110, v110, s0
	ds_write_b16 v146, v110 offset:16384
	v_sub_u32_e32 v110, v133, v114
	v_cvt_f32_u32_e32 v115, v110
	v_cmp_lt_i32_e32 vcc, -1, v110
	v_mul_f32_e32 v115, v115, v131
	v_mul_f32_e32 v115, 0xbfb8aa3b, v115
	v_exp_f32_e32 v115, v115
	s_nop 0
	v_add_f32_e32 v115, 0, v115
	v_cndmask_b32_e32 v116, 0, v115, vcc
	v_cmp_gt_i32_e32 vcc, 1, v110
	v_sub_u32_e32 v110, 0, v110
	v_cvt_f32_u32_e32 v110, v110
	v_mul_f32_e32 v110, v110, v130
	v_mul_f32_e32 v110, 0xbfb8aa3b, v110
	v_exp_f32_e32 v110, v110
	s_nop 0
	v_add_f32_e32 v110, v110, v116
	v_cndmask_b32_e32 v110, v115, v110, vcc
	v_mul_f32_e32 v110, v110, v111
	v_cvt_pk_bf16_f32 v110, v110, s0
	ds_write_b16 v147, v110 offset:16384
	v_sub_u32_e32 v110, v127, v114
	v_cvt_f32_u32_e32 v111, v110
	v_cmp_lt_i32_e32 vcc, -1, v110
	v_mul_f32_e32 v111, v111, v131
	v_mul_f32_e32 v111, 0xbfb8aa3b, v111
	v_exp_f32_e32 v111, v111
	s_nop 0
	v_add_f32_e32 v111, 0, v111
	v_cndmask_b32_e32 v115, 0, v111, vcc
	v_cmp_gt_i32_e32 vcc, 1, v110
	v_sub_u32_e32 v110, 0, v110
	v_cvt_f32_u32_e32 v110, v110
	v_mul_f32_e32 v110, v110, v130
	v_mul_f32_e32 v110, 0xbfb8aa3b, v110
	v_exp_f32_e32 v110, v110
	s_nop 0
	v_add_f32_e32 v110, v110, v115
	v_cndmask_b32_e32 v110, v111, v110, vcc
	v_mul_f32_e32 v110, v110, v112
	v_cvt_pk_bf16_f32 v110, v110, s0
	ds_write_b16 v148, v110 offset:16384
	v_sub_u32_e32 v110, v126, v114
	v_cvt_f32_u32_e32 v111, v110
	v_cmp_lt_i32_e32 vcc, -1, v110
	v_or_b32_e32 v115, 16, v132
	v_mul_f32_e32 v111, v111, v131
	v_mul_f32_e32 v111, 0xbfb8aa3b, v111
	v_exp_f32_e32 v111, v111
	s_nop 0
	v_add_f32_e32 v111, 0, v111
	v_cndmask_b32_e32 v112, 0, v111, vcc
	v_cmp_gt_i32_e32 vcc, 1, v110
	v_sub_u32_e32 v110, 0, v110
	v_cvt_f32_u32_e32 v110, v110
	v_mul_f32_e32 v110, v110, v130
	v_mul_f32_e32 v110, 0xbfb8aa3b, v110
	v_exp_f32_e32 v110, v110
	s_nop 0
	v_add_f32_e32 v110, v110, v112
	v_cndmask_b32_e32 v110, v111, v110, vcc
	v_mul_f32_e32 v110, v110, v113
	v_cvt_pk_bf16_f32 v110, v110, s0
	v_or_b32_e32 v113, 0x50, v0
	ds_write_b16 v149, v110 offset:16384
	v_sub_u32_e32 v110, v132, v113
	v_cvt_f32_u32_e32 v111, v110
	v_cmp_lt_i32_e32 vcc, -1, v110
	v_mul_f32_e32 v111, v111, v131
	v_mul_f32_e32 v111, 0xbfb8aa3b, v111
	v_exp_f32_e32 v111, v111
	s_nop 0
	v_add_f32_e32 v111, 0, v111
	v_cndmask_b32_e32 v112, 0, v111, vcc
	v_cmp_gt_i32_e32 vcc, 1, v110
	v_sub_u32_e32 v110, 0, v110
	v_cvt_f32_u32_e32 v110, v110
	v_mul_f32_e32 v110, v110, v130
	v_mul_f32_e32 v110, 0xbfb8aa3b, v110
	v_exp_f32_e32 v110, v110
	s_nop 0
	v_add_f32_e32 v110, v110, v112
	v_cndmask_b32_e32 v110, v111, v110, vcc
	v_mul_f32_e32 v106, v110, v106
	v_bitop3_b32 v110, v139, 56, v113 bitop3:0x48
	v_lshl_add_u32 v110, v110, 1, 0
	v_cvt_pk_bf16_f32 v106, v106, s0
	v_add3_u32 v110, v110, v140, v137
	ds_write_b16 v110, v106 offset:16384
	v_sub_u32_e32 v106, v133, v113
	v_cvt_f32_u32_e32 v110, v106
	v_cmp_lt_i32_e32 vcc, -1, v106
	v_or_b32_e32 v112, 17, v132
	v_mul_f32_e32 v110, v110, v131
	v_mul_f32_e32 v110, 0xbfb8aa3b, v110
	v_exp_f32_e32 v110, v110
	s_nop 0
	v_add_f32_e32 v110, 0, v110
	v_cndmask_b32_e32 v111, 0, v110, vcc
	v_cmp_gt_i32_e32 vcc, 1, v106
	v_sub_u32_e32 v106, 0, v106
	v_cvt_f32_u32_e32 v106, v106
	v_mul_f32_e32 v106, v106, v130
	v_mul_f32_e32 v106, 0xbfb8aa3b, v106
	v_exp_f32_e32 v106, v106
	s_nop 0
	v_add_f32_e32 v106, v106, v111
	v_cndmask_b32_e32 v106, v110, v106, vcc
	v_mul_f32_e32 v106, v106, v107
	v_bitop3_b32 v107, v141, 56, v113 bitop3:0x48
	v_lshl_add_u32 v107, v107, 1, 0
	v_cvt_pk_bf16_f32 v106, v106, s0
	v_add3_u32 v107, v107, v142, v137
	ds_write_b16 v107, v106 offset:16384
	v_sub_u32_e32 v106, v127, v113
	v_cvt_f32_u32_e32 v107, v106
	v_cmp_lt_i32_e32 vcc, -1, v106
	v_or_b32_e32 v111, 18, v132
	v_mul_f32_e32 v107, v107, v131
	v_mul_f32_e32 v107, 0xbfb8aa3b, v107
	v_exp_f32_e32 v107, v107
	s_nop 0
	v_add_f32_e32 v107, 0, v107
	v_cndmask_b32_e32 v110, 0, v107, vcc
	v_cmp_gt_i32_e32 vcc, 1, v106
	v_sub_u32_e32 v106, 0, v106
	v_cvt_f32_u32_e32 v106, v106
	v_mul_f32_e32 v106, v106, v130
	v_mul_f32_e32 v106, 0xbfb8aa3b, v106
	v_exp_f32_e32 v106, v106
	s_nop 0
	v_add_f32_e32 v106, v106, v110
	v_cndmask_b32_e32 v106, v107, v106, vcc
	v_bitop3_b32 v107, v143, 56, v113 bitop3:0x48
	v_mul_f32_e32 v106, v106, v108
	v_lshl_add_u32 v107, v107, 1, 0
	v_cvt_pk_bf16_f32 v106, v106, s0
	v_add3_u32 v107, v107, v144, v137
	ds_write_b16 v107, v106 offset:16384
	v_sub_u32_e32 v106, v126, v113
	v_cvt_f32_u32_e32 v107, v106
	v_cmp_lt_i32_e32 vcc, -1, v106
	v_or_b32_e32 v110, 19, v132
	v_mul_f32_e32 v107, v107, v131
	v_mul_f32_e32 v107, 0xbfb8aa3b, v107
	v_exp_f32_e32 v107, v107
	s_nop 0
	v_add_f32_e32 v107, 0, v107
	v_cndmask_b32_e32 v108, 0, v107, vcc
	v_cmp_gt_i32_e32 vcc, 1, v106
	v_sub_u32_e32 v106, 0, v106
	v_cvt_f32_u32_e32 v106, v106
	v_mul_f32_e32 v106, v106, v130
	v_mul_f32_e32 v106, 0xbfb8aa3b, v106
	v_exp_f32_e32 v106, v106
	s_nop 0
	v_add_f32_e32 v106, v106, v108
	v_cndmask_b32_e32 v106, v107, v106, vcc
	v_bitop3_b32 v107, v129, 56, v113 bitop3:0x48
	v_mul_f32_e32 v106, v106, v109
	v_lshl_add_u32 v107, v107, 1, 0
	v_cvt_pk_bf16_f32 v106, v106, s0
	v_add3_u32 v107, v107, v145, v137
	ds_write_b16 v107, v106 offset:16384
	v_or_b32_e32 v106, 0x60, v0
	v_sub_u32_e32 v107, v132, v106
	v_cvt_f32_u32_e32 v108, v107
	v_cmp_lt_i32_e32 vcc, -1, v107
	v_mul_f32_e32 v108, v108, v131
	v_mul_f32_e32 v108, 0xbfb8aa3b, v108
	v_exp_f32_e32 v108, v108
	s_nop 0
	v_add_f32_e32 v108, 0, v108
	v_cndmask_b32_e32 v109, 0, v108, vcc
	v_cmp_gt_i32_e32 vcc, 1, v107
	v_sub_u32_e32 v107, 0, v107
	v_cvt_f32_u32_e32 v107, v107
	v_mul_f32_e32 v107, v107, v130
	v_mul_f32_e32 v107, 0xbfb8aa3b, v107
	v_exp_f32_e32 v107, v107
	s_nop 0
	v_add_f32_e32 v107, v107, v109
	v_cndmask_b32_e32 v107, v108, v107, vcc
	v_mul_f32_e32 v102, v107, v102
	v_bitop3_b32 v107, v139, 56, v106 bitop3:0x48
	v_lshl_add_u32 v107, v107, 1, 0
	v_cvt_pk_bf16_f32 v102, v102, s0
	v_add3_u32 v107, v107, v140, v137
	ds_write_b16 v107, v102 offset:16384
	v_sub_u32_e32 v102, v133, v106
	v_cvt_f32_u32_e32 v107, v102
	v_cmp_lt_i32_e32 vcc, -1, v102
	v_mul_f32_e32 v107, v107, v131
	v_mul_f32_e32 v107, 0xbfb8aa3b, v107
	v_exp_f32_e32 v107, v107
	s_nop 0
	v_add_f32_e32 v107, 0, v107
	v_cndmask_b32_e32 v108, 0, v107, vcc
	v_cmp_gt_i32_e32 vcc, 1, v102
	v_sub_u32_e32 v102, 0, v102
	v_cvt_f32_u32_e32 v102, v102
	v_mul_f32_e32 v102, v102, v130
	v_mul_f32_e32 v102, 0xbfb8aa3b, v102
	v_exp_f32_e32 v102, v102
	s_nop 0
	v_add_f32_e32 v102, v102, v108
	v_cndmask_b32_e32 v102, v107, v102, vcc
	v_mul_f32_e32 v102, v102, v103
	v_bitop3_b32 v103, v141, 56, v106 bitop3:0x48
	v_lshl_add_u32 v103, v103, 1, 0
	v_cvt_pk_bf16_f32 v102, v102, s0
	v_add3_u32 v103, v103, v142, v137
	ds_write_b16 v103, v102 offset:16384
	v_sub_u32_e32 v102, v127, v106
	v_cvt_f32_u32_e32 v103, v102
	v_cmp_lt_i32_e32 vcc, -1, v102
	v_mul_f32_e32 v103, v103, v131
	v_mul_f32_e32 v103, 0xbfb8aa3b, v103
	v_exp_f32_e32 v103, v103
	s_nop 0
	v_add_f32_e32 v103, 0, v103
	v_cndmask_b32_e32 v107, 0, v103, vcc
	v_cmp_gt_i32_e32 vcc, 1, v102
	v_sub_u32_e32 v102, 0, v102
	v_cvt_f32_u32_e32 v102, v102
	v_mul_f32_e32 v102, v102, v130
	v_mul_f32_e32 v102, 0xbfb8aa3b, v102
	v_exp_f32_e32 v102, v102
	s_nop 0
	v_add_f32_e32 v102, v102, v107
	v_cndmask_b32_e32 v102, v103, v102, vcc
	v_bitop3_b32 v103, v143, 56, v106 bitop3:0x48
	v_mul_f32_e32 v102, v102, v104
	v_lshl_add_u32 v103, v103, 1, 0
	v_cvt_pk_bf16_f32 v102, v102, s0
	v_add3_u32 v103, v103, v144, v137
	ds_write_b16 v103, v102 offset:16384
	v_sub_u32_e32 v102, v126, v106
	v_cvt_f32_u32_e32 v103, v102
	v_cmp_lt_i32_e32 vcc, -1, v102
	v_mul_f32_e32 v103, v103, v131
	v_mul_f32_e32 v103, 0xbfb8aa3b, v103
	v_exp_f32_e32 v103, v103
	s_nop 0
	v_add_f32_e32 v103, 0, v103
	v_cndmask_b32_e32 v104, 0, v103, vcc
	v_cmp_gt_i32_e32 vcc, 1, v102
	v_sub_u32_e32 v102, 0, v102
	v_cvt_f32_u32_e32 v102, v102
	v_mul_f32_e32 v102, v102, v130
	v_mul_f32_e32 v102, 0xbfb8aa3b, v102
	v_exp_f32_e32 v102, v102
	s_nop 0
	v_add_f32_e32 v102, v102, v104
	v_cndmask_b32_e32 v102, v103, v102, vcc
	v_bitop3_b32 v103, v129, 56, v106 bitop3:0x48
	v_mul_f32_e32 v102, v102, v105
	v_lshl_add_u32 v103, v103, 1, 0
	v_cvt_pk_bf16_f32 v102, v102, s0
	v_add3_u32 v103, v103, v145, v137
	ds_write_b16 v103, v102 offset:16384
	v_or_b32_e32 v102, 0x70, v0
	v_sub_u32_e32 v103, v132, v102
	v_cvt_f32_u32_e32 v104, v103
	v_cmp_lt_i32_e32 vcc, -1, v103
	v_mul_f32_e32 v104, v104, v131
	v_mul_f32_e32 v104, 0xbfb8aa3b, v104
	v_exp_f32_e32 v104, v104
	s_nop 0
	v_add_f32_e32 v104, 0, v104
	v_cndmask_b32_e32 v105, 0, v104, vcc
	v_cmp_gt_i32_e32 vcc, 1, v103
	v_sub_u32_e32 v103, 0, v103
	v_cvt_f32_u32_e32 v103, v103
	v_mul_f32_e32 v103, v103, v130
	v_mul_f32_e32 v103, 0xbfb8aa3b, v103
	v_exp_f32_e32 v103, v103
	s_nop 0
	v_add_f32_e32 v103, v103, v105
	v_cndmask_b32_e32 v103, v104, v103, vcc
	v_mul_f32_e32 v98, v103, v98
	v_bitop3_b32 v103, v139, 56, v102 bitop3:0x48
	v_lshl_add_u32 v103, v103, 1, 0
	v_cvt_pk_bf16_f32 v98, v98, s0
	v_add3_u32 v103, v103, v140, v137
	ds_write_b16 v103, v98 offset:16384
	v_sub_u32_e32 v98, v133, v102
	v_cvt_f32_u32_e32 v103, v98
	v_cmp_lt_i32_e32 vcc, -1, v98
	v_mul_f32_e32 v103, v103, v131
	v_mul_f32_e32 v103, 0xbfb8aa3b, v103
	v_exp_f32_e32 v103, v103
	s_nop 0
	v_add_f32_e32 v103, 0, v103
	v_cndmask_b32_e32 v104, 0, v103, vcc
	v_cmp_gt_i32_e32 vcc, 1, v98
	v_sub_u32_e32 v98, 0, v98
	v_cvt_f32_u32_e32 v98, v98
	v_mul_f32_e32 v98, v98, v130
	v_mul_f32_e32 v98, 0xbfb8aa3b, v98
	v_exp_f32_e32 v98, v98
	s_nop 0
	v_add_f32_e32 v98, v98, v104
	v_cndmask_b32_e32 v98, v103, v98, vcc
	v_mul_f32_e32 v98, v98, v99
	v_bitop3_b32 v99, v141, 56, v102 bitop3:0x48
	v_lshl_add_u32 v99, v99, 1, 0
	v_cvt_pk_bf16_f32 v98, v98, s0
	v_add3_u32 v99, v99, v142, v137
	ds_write_b16 v99, v98 offset:16384
	v_sub_u32_e32 v98, v127, v102
	v_cvt_f32_u32_e32 v99, v98
	v_cmp_lt_i32_e32 vcc, -1, v98
	v_mul_f32_e32 v99, v99, v131
	v_mul_f32_e32 v99, 0xbfb8aa3b, v99
	v_exp_f32_e32 v99, v99
	s_nop 0
	v_add_f32_e32 v99, 0, v99
	v_cndmask_b32_e32 v103, 0, v99, vcc
	v_cmp_gt_i32_e32 vcc, 1, v98
	v_sub_u32_e32 v98, 0, v98
	v_cvt_f32_u32_e32 v98, v98
	v_mul_f32_e32 v98, v98, v130
	v_mul_f32_e32 v98, 0xbfb8aa3b, v98
	v_exp_f32_e32 v98, v98
	s_nop 0
	v_add_f32_e32 v98, v98, v103
	v_cndmask_b32_e32 v98, v99, v98, vcc
	v_bitop3_b32 v99, v143, 56, v102 bitop3:0x48
	v_mul_f32_e32 v98, v98, v100
	v_lshl_add_u32 v99, v99, 1, 0
	v_cvt_pk_bf16_f32 v98, v98, s0
	v_add3_u32 v99, v99, v144, v137
	ds_write_b16 v99, v98 offset:16384
	v_sub_u32_e32 v98, v126, v102
	v_cvt_f32_u32_e32 v99, v98
	v_cmp_lt_i32_e32 vcc, -1, v98
	v_mul_f32_e32 v99, v99, v131
	v_mul_f32_e32 v99, 0xbfb8aa3b, v99
	v_exp_f32_e32 v99, v99
	s_nop 0
	v_add_f32_e32 v99, 0, v99
	v_cndmask_b32_e32 v100, 0, v99, vcc
	v_cmp_gt_i32_e32 vcc, 1, v98
	v_sub_u32_e32 v98, 0, v98
	v_cvt_f32_u32_e32 v98, v98
	v_mul_f32_e32 v98, v98, v130
	v_mul_f32_e32 v98, 0xbfb8aa3b, v98
	v_exp_f32_e32 v98, v98
	s_nop 0
	v_add_f32_e32 v98, v98, v100
	v_cndmask_b32_e32 v98, v99, v98, vcc
	v_bitop3_b32 v99, v129, 56, v102 bitop3:0x48
	v_mul_f32_e32 v98, v98, v101
	v_lshl_add_u32 v99, v99, 1, 0
	v_cvt_pk_bf16_f32 v98, v98, s0
	v_add3_u32 v99, v99, v145, v137
	ds_write_b16 v99, v98 offset:16384
	v_sub_u32_e32 v98, v115, v0
	v_cvt_f32_u32_e32 v99, v98
	v_cmp_lt_i32_e32 vcc, -1, v98
	v_mul_f32_e32 v99, v99, v131
	v_mul_f32_e32 v99, 0xbfb8aa3b, v99
	v_exp_f32_e32 v99, v99
	s_nop 0
	v_add_f32_e32 v99, 0, v99
	v_cndmask_b32_e32 v100, 0, v99, vcc
	v_cmp_gt_i32_e32 vcc, 1, v98
	v_sub_u32_e32 v98, 0, v98
	v_cvt_f32_u32_e32 v98, v98
	v_mul_f32_e32 v98, v98, v130
	v_mul_f32_e32 v98, 0xbfb8aa3b, v98
	v_exp_f32_e32 v98, v98
	s_nop 0
	v_add_f32_e32 v98, v98, v100
	v_cndmask_b32_e32 v98, v99, v98, vcc
	v_mul_f32_e32 v94, v98, v94
	v_cvt_pk_bf16_f32 v99, v94, s0
	v_lshlrev_b32_e32 v94, 2, v115
	v_bitop3_b32 v98, v94, 56, v0 bitop3:0xc8
	v_lshl_add_u32 v100, v98, 1, 0
	v_lshlrev_b32_e32 v98, 7, v115
	v_add3_u32 v103, v100, v98, v137
	ds_write_b16 v103, v99
	v_sub_u32_e32 v99, v112, v0
	v_cvt_f32_u32_e32 v100, v99
	v_cmp_lt_i32_e32 vcc, -1, v99
	v_mul_f32_e32 v100, v100, v131
	v_mul_f32_e32 v100, 0xbfb8aa3b, v100
	v_exp_f32_e32 v100, v100
	s_nop 0
	v_add_f32_e32 v100, 0, v100
	v_cndmask_b32_e32 v101, 0, v100, vcc
	v_cmp_gt_i32_e32 vcc, 1, v99
	v_sub_u32_e32 v99, 0, v99
	v_cvt_f32_u32_e32 v99, v99
	v_mul_f32_e32 v99, v99, v130
	v_mul_f32_e32 v99, 0xbfb8aa3b, v99
	v_exp_f32_e32 v99, v99
	s_nop 0
	v_add_f32_e32 v99, v99, v101
	v_cndmask_b32_e32 v99, v100, v99, vcc
	v_mul_f32_e32 v95, v99, v95
	v_cvt_pk_bf16_f32 v100, v95, s0
	v_lshlrev_b32_e32 v95, 2, v112
	v_bitop3_b32 v99, v95, 56, v0 bitop3:0xc8
	v_lshl_add_u32 v101, v99, 1, 0
	v_lshlrev_b32_e32 v99, 7, v112
	v_add3_u32 v104, v101, v99, v137
	ds_write_b16 v104, v100
	v_sub_u32_e32 v100, v111, v0
	v_cvt_f32_u32_e32 v101, v100
	v_cmp_lt_i32_e32 vcc, -1, v100
	v_mul_f32_e32 v101, v101, v131
	v_mul_f32_e32 v101, 0xbfb8aa3b, v101
	v_exp_f32_e32 v101, v101
	s_nop 0
	v_add_f32_e32 v101, 0, v101
	v_cndmask_b32_e32 v105, 0, v101, vcc
	v_cmp_gt_i32_e32 vcc, 1, v100
	v_sub_u32_e32 v100, 0, v100
	v_cvt_f32_u32_e32 v100, v100
	v_mul_f32_e32 v100, v100, v130
	v_mul_f32_e32 v100, 0xbfb8aa3b, v100
	v_exp_f32_e32 v100, v100
	s_nop 0
	v_add_f32_e32 v100, v100, v105
	v_cndmask_b32_e32 v100, v101, v100, vcc
	v_mul_f32_e32 v96, v100, v96
	v_cvt_pk_bf16_f32 v101, v96, s0
	v_lshlrev_b32_e32 v96, 2, v111
	v_bitop3_b32 v100, v96, 56, v0 bitop3:0x48
	v_lshl_add_u32 v105, v100, 1, 0
	v_lshlrev_b32_e32 v100, 7, v111
	v_add3_u32 v105, v105, v100, v137
	ds_write_b16 v105, v101
	v_sub_u32_e32 v101, v110, v0
	v_cvt_f32_u32_e32 v107, v101
	v_cmp_lt_i32_e32 vcc, -1, v101
	v_mul_f32_e32 v107, v107, v131
	v_mul_f32_e32 v107, 0xbfb8aa3b, v107
	v_exp_f32_e32 v107, v107
	s_nop 0
	v_add_f32_e32 v107, 0, v107
	v_cndmask_b32_e32 v108, 0, v107, vcc
	v_cmp_gt_i32_e32 vcc, 1, v101
	v_sub_u32_e32 v101, 0, v101
	v_cvt_f32_u32_e32 v101, v101
	v_mul_f32_e32 v101, v101, v130
	v_mul_f32_e32 v101, 0xbfb8aa3b, v101
	v_exp_f32_e32 v101, v101
	s_nop 0
	v_add_f32_e32 v101, v101, v108
	v_cndmask_b32_e32 v101, v107, v101, vcc
	v_mul_f32_e32 v97, v101, v97
	v_cvt_pk_bf16_f32 v108, v97, s0
	v_lshlrev_b32_e32 v97, 2, v110
	v_bitop3_b32 v101, v97, 56, v0 bitop3:0x48
	v_lshl_add_u32 v107, v101, 1, 0
	v_lshlrev_b32_e32 v101, 7, v110
	v_add3_u32 v107, v107, v101, v137
	ds_write_b16 v107, v108
	v_bitop3_b32 v108, v94, 56, v128 bitop3:0x48
	v_lshl_add_u32 v108, v108, 1, 0
	v_add3_u32 v108, v108, v98, v137
	ds_write_b16 v108, v90
	v_sub_u32_e32 v90, v112, v128
	v_cvt_f32_u32_e32 v108, v90
	v_cmp_lt_i32_e32 vcc, -1, v90
	v_lshlrev_b32_e32 v0, 1, v0
	v_mul_f32_e32 v108, v108, v131
	v_mul_f32_e32 v108, 0xbfb8aa3b, v108
	v_exp_f32_e32 v108, v108
	s_nop 0
	v_add_f32_e32 v108, 0, v108
	v_cndmask_b32_e32 v109, 0, v108, vcc
	v_cmp_gt_i32_e32 vcc, 1, v90
	v_sub_u32_e32 v90, 0, v90
	v_cvt_f32_u32_e32 v90, v90
	v_mul_f32_e32 v90, v90, v130
	v_mul_f32_e32 v90, 0xbfb8aa3b, v90
	v_exp_f32_e32 v90, v90
	s_nop 0
	v_add_f32_e32 v90, v90, v109
	v_cndmask_b32_e32 v90, v108, v90, vcc
	v_mul_f32_e32 v90, v90, v91
	v_bitop3_b32 v91, v95, 56, v128 bitop3:0x48
	v_lshl_add_u32 v91, v91, 1, 0
	v_cvt_pk_bf16_f32 v90, v90, s0
	v_add3_u32 v91, v91, v99, v137
	ds_write_b16 v91, v90
	v_sub_u32_e32 v90, v111, v128
	v_cvt_f32_u32_e32 v91, v90
	v_cmp_lt_i32_e32 vcc, -1, v90
	v_mul_f32_e32 v91, v91, v131
	v_mul_f32_e32 v91, 0xbfb8aa3b, v91
	v_exp_f32_e32 v91, v91
	s_nop 0
	v_add_f32_e32 v91, 0, v91
	v_cndmask_b32_e32 v108, 0, v91, vcc
	v_cmp_gt_i32_e32 vcc, 1, v90
	v_sub_u32_e32 v90, 0, v90
	v_cvt_f32_u32_e32 v90, v90
	v_mul_f32_e32 v90, v90, v130
	v_mul_f32_e32 v90, 0xbfb8aa3b, v90
	v_exp_f32_e32 v90, v90
	s_nop 0
	v_add_f32_e32 v90, v90, v108
	v_cndmask_b32_e32 v90, v91, v90, vcc
	v_bitop3_b32 v91, v96, 56, v128 bitop3:0x48
	v_mul_f32_e32 v90, v90, v92
	v_lshl_add_u32 v91, v91, 1, 0
	v_cvt_pk_bf16_f32 v90, v90, s0
	v_add3_u32 v91, v91, v100, v137
	ds_write_b16 v91, v90
	v_sub_u32_e32 v90, v110, v128
	v_cvt_f32_u32_e32 v91, v90
	v_cmp_lt_i32_e32 vcc, -1, v90
	v_mul_f32_e32 v91, v91, v131
	v_mul_f32_e32 v91, 0xbfb8aa3b, v91
	v_exp_f32_e32 v91, v91
	s_nop 0
	v_add_f32_e32 v91, 0, v91
	v_cndmask_b32_e32 v92, 0, v91, vcc
	v_cmp_gt_i32_e32 vcc, 1, v90
	v_sub_u32_e32 v90, 0, v90
	v_cvt_f32_u32_e32 v90, v90
	v_mul_f32_e32 v90, v90, v130
	v_mul_f32_e32 v90, 0xbfb8aa3b, v90
	v_exp_f32_e32 v90, v90
	s_nop 0
	v_add_f32_e32 v90, v90, v92
	v_cndmask_b32_e32 v90, v91, v90, vcc
	v_bitop3_b32 v91, v97, 56, v128 bitop3:0x48
	v_mul_f32_e32 v90, v90, v93
	v_lshl_add_u32 v91, v91, 1, 0
	v_cvt_pk_bf16_f32 v90, v90, s0
	v_add3_u32 v91, v91, v101, v137
	ds_write_b16 v91, v90
	v_sub_u32_e32 v90, v115, v122
	v_cvt_f32_u32_e32 v91, v90
	v_cmp_lt_i32_e32 vcc, -1, v90
	v_mul_f32_e32 v91, v91, v131
	v_mul_f32_e32 v91, 0xbfb8aa3b, v91
	v_exp_f32_e32 v91, v91
	s_nop 0
	v_add_f32_e32 v91, 0, v91
	v_cndmask_b32_e32 v92, 0, v91, vcc
	v_cmp_gt_i32_e32 vcc, 1, v90
	v_sub_u32_e32 v90, 0, v90
	v_cvt_f32_u32_e32 v90, v90
	v_mul_f32_e32 v90, v90, v130
	v_mul_f32_e32 v90, 0xbfb8aa3b, v90
	v_exp_f32_e32 v90, v90
	s_nop 0
	v_add_f32_e32 v90, v90, v92
	v_cndmask_b32_e32 v90, v91, v90, vcc
	v_mul_f32_e32 v86, v90, v86
	v_bitop3_b32 v90, v94, 56, v122 bitop3:0x48
	v_lshl_add_u32 v90, v90, 1, 0
	v_cvt_pk_bf16_f32 v86, v86, s0
	v_add3_u32 v90, v90, v98, v137
	ds_write_b16 v90, v86
	v_sub_u32_e32 v86, v112, v122
	v_cvt_f32_u32_e32 v90, v86
	v_cmp_lt_i32_e32 vcc, -1, v86
	v_mul_f32_e32 v90, v90, v131
	v_mul_f32_e32 v90, 0xbfb8aa3b, v90
	v_exp_f32_e32 v90, v90
	s_nop 0
	v_add_f32_e32 v90, 0, v90
	v_cndmask_b32_e32 v91, 0, v90, vcc
	v_cmp_gt_i32_e32 vcc, 1, v86
	v_sub_u32_e32 v86, 0, v86
	v_cvt_f32_u32_e32 v86, v86
	v_mul_f32_e32 v86, v86, v130
	v_mul_f32_e32 v86, 0xbfb8aa3b, v86
	v_exp_f32_e32 v86, v86
	s_nop 0
	v_add_f32_e32 v86, v86, v91
	v_cndmask_b32_e32 v86, v90, v86, vcc
	v_mul_f32_e32 v86, v86, v87
	v_bitop3_b32 v87, v95, 56, v122 bitop3:0x48
	v_lshl_add_u32 v87, v87, 1, 0
	v_cvt_pk_bf16_f32 v86, v86, s0
	v_add3_u32 v87, v87, v99, v137
	ds_write_b16 v87, v86
	v_sub_u32_e32 v86, v111, v122
	v_cvt_f32_u32_e32 v87, v86
	v_cmp_lt_i32_e32 vcc, -1, v86
	v_mul_f32_e32 v87, v87, v131
	v_mul_f32_e32 v87, 0xbfb8aa3b, v87
	v_exp_f32_e32 v87, v87
	s_nop 0
	v_add_f32_e32 v87, 0, v87
	v_cndmask_b32_e32 v90, 0, v87, vcc
	v_cmp_gt_i32_e32 vcc, 1, v86
	v_sub_u32_e32 v86, 0, v86
	v_cvt_f32_u32_e32 v86, v86
	v_mul_f32_e32 v86, v86, v130
	v_mul_f32_e32 v86, 0xbfb8aa3b, v86
	v_exp_f32_e32 v86, v86
	s_nop 0
	v_add_f32_e32 v86, v86, v90
	v_cndmask_b32_e32 v86, v87, v86, vcc
	v_bitop3_b32 v87, v96, 56, v122 bitop3:0x48
	v_mul_f32_e32 v86, v86, v88
	v_lshl_add_u32 v87, v87, 1, 0
	v_cvt_pk_bf16_f32 v86, v86, s0
	v_add3_u32 v87, v87, v100, v137
	ds_write_b16 v87, v86
	v_sub_u32_e32 v86, v110, v122
	v_cvt_f32_u32_e32 v87, v86
	v_cmp_lt_i32_e32 vcc, -1, v86
	v_mul_f32_e32 v87, v87, v131
	v_mul_f32_e32 v87, 0xbfb8aa3b, v87
	v_exp_f32_e32 v87, v87
	s_nop 0
	v_add_f32_e32 v87, 0, v87
	v_cndmask_b32_e32 v88, 0, v87, vcc
	v_cmp_gt_i32_e32 vcc, 1, v86
	v_sub_u32_e32 v86, 0, v86
	v_cvt_f32_u32_e32 v86, v86
	v_mul_f32_e32 v86, v86, v130
	v_mul_f32_e32 v86, 0xbfb8aa3b, v86
	v_exp_f32_e32 v86, v86
	s_nop 0
	v_add_f32_e32 v86, v86, v88
	v_cndmask_b32_e32 v86, v87, v86, vcc
	v_bitop3_b32 v87, v97, 56, v122 bitop3:0x48
	v_mul_f32_e32 v86, v86, v89
	v_lshl_add_u32 v87, v87, 1, 0
	v_cvt_pk_bf16_f32 v86, v86, s0
	v_add3_u32 v87, v87, v101, v137
	ds_write_b16 v87, v86
	v_sub_u32_e32 v86, v115, v118
	v_cvt_f32_u32_e32 v87, v86
	v_cmp_lt_i32_e32 vcc, -1, v86
	v_mul_f32_e32 v87, v87, v131
	v_mul_f32_e32 v87, 0xbfb8aa3b, v87
	v_exp_f32_e32 v87, v87
	s_nop 0
	v_add_f32_e32 v87, 0, v87
	v_cndmask_b32_e32 v88, 0, v87, vcc
	v_cmp_gt_i32_e32 vcc, 1, v86
	v_sub_u32_e32 v86, 0, v86
	v_cvt_f32_u32_e32 v86, v86
	v_mul_f32_e32 v86, v86, v130
	v_mul_f32_e32 v86, 0xbfb8aa3b, v86
	v_exp_f32_e32 v86, v86
	s_nop 0
	v_add_f32_e32 v86, v86, v88
	v_cndmask_b32_e32 v86, v87, v86, vcc
	v_mul_f32_e32 v82, v86, v82
	v_bitop3_b32 v86, v94, 56, v118 bitop3:0x48
	v_lshl_add_u32 v86, v86, 1, 0
	v_cvt_pk_bf16_f32 v82, v82, s0
	v_add3_u32 v86, v86, v98, v137
	ds_write_b16 v86, v82
	v_sub_u32_e32 v82, v112, v118
	v_cvt_f32_u32_e32 v86, v82
	v_cmp_lt_i32_e32 vcc, -1, v82
	v_mul_f32_e32 v86, v86, v131
	v_mul_f32_e32 v86, 0xbfb8aa3b, v86
	v_exp_f32_e32 v86, v86
	s_nop 0
	v_add_f32_e32 v86, 0, v86
	v_cndmask_b32_e32 v87, 0, v86, vcc
	v_cmp_gt_i32_e32 vcc, 1, v82
	v_sub_u32_e32 v82, 0, v82
	v_cvt_f32_u32_e32 v82, v82
	v_mul_f32_e32 v82, v82, v130
	v_mul_f32_e32 v82, 0xbfb8aa3b, v82
	v_exp_f32_e32 v82, v82
	s_nop 0
	v_add_f32_e32 v82, v82, v87
	v_cndmask_b32_e32 v82, v86, v82, vcc
	v_mul_f32_e32 v82, v82, v83
	v_bitop3_b32 v83, v95, 56, v118 bitop3:0x48
	v_lshl_add_u32 v83, v83, 1, 0
	v_cvt_pk_bf16_f32 v82, v82, s0
	v_add3_u32 v83, v83, v99, v137
	ds_write_b16 v83, v82
	v_sub_u32_e32 v82, v111, v118
	v_cvt_f32_u32_e32 v83, v82
	v_cmp_lt_i32_e32 vcc, -1, v82
	v_mul_f32_e32 v83, v83, v131
	v_mul_f32_e32 v83, 0xbfb8aa3b, v83
	v_exp_f32_e32 v83, v83
	s_nop 0
	v_add_f32_e32 v83, 0, v83
	v_cndmask_b32_e32 v86, 0, v83, vcc
	v_cmp_gt_i32_e32 vcc, 1, v82
	v_sub_u32_e32 v82, 0, v82
	v_cvt_f32_u32_e32 v82, v82
	v_mul_f32_e32 v82, v82, v130
	v_mul_f32_e32 v82, 0xbfb8aa3b, v82
	v_exp_f32_e32 v82, v82
	s_nop 0
	v_add_f32_e32 v82, v82, v86
	v_cndmask_b32_e32 v82, v83, v82, vcc
	v_bitop3_b32 v83, v96, 56, v118 bitop3:0x48
	v_mul_f32_e32 v82, v82, v84
	v_lshl_add_u32 v83, v83, 1, 0
	v_cvt_pk_bf16_f32 v82, v82, s0
	v_add3_u32 v83, v83, v100, v137
	ds_write_b16 v83, v82
	v_sub_u32_e32 v82, v110, v118
	v_cvt_f32_u32_e32 v83, v82
	v_cmp_lt_i32_e32 vcc, -1, v82
	v_mul_f32_e32 v83, v83, v131
	v_mul_f32_e32 v83, 0xbfb8aa3b, v83
	v_exp_f32_e32 v83, v83
	s_nop 0
	v_add_f32_e32 v83, 0, v83
	v_cndmask_b32_e32 v84, 0, v83, vcc
	v_cmp_gt_i32_e32 vcc, 1, v82
	v_sub_u32_e32 v82, 0, v82
	v_cvt_f32_u32_e32 v82, v82
	v_mul_f32_e32 v82, v82, v130
	v_mul_f32_e32 v82, 0xbfb8aa3b, v82
	v_exp_f32_e32 v82, v82
	s_nop 0
	v_add_f32_e32 v82, v82, v84
	v_cndmask_b32_e32 v82, v83, v82, vcc
	v_bitop3_b32 v83, v97, 56, v118 bitop3:0x48
	v_mul_f32_e32 v82, v82, v85
	v_lshl_add_u32 v83, v83, 1, 0
	v_cvt_pk_bf16_f32 v82, v82, s0
	v_add3_u32 v83, v83, v101, v137
	ds_write_b16 v83, v82
	v_sub_u32_e32 v82, v115, v114
	v_cvt_f32_u32_e32 v83, v82
	v_cmp_lt_i32_e32 vcc, -1, v82
	v_mul_f32_e32 v83, v83, v131
	v_mul_f32_e32 v83, 0xbfb8aa3b, v83
	v_exp_f32_e32 v83, v83
	s_nop 0
	v_add_f32_e32 v83, 0, v83
	v_cndmask_b32_e32 v84, 0, v83, vcc
	v_cmp_gt_i32_e32 vcc, 1, v82
	v_sub_u32_e32 v82, 0, v82
	v_cvt_f32_u32_e32 v82, v82
	v_mul_f32_e32 v82, v82, v130
	v_mul_f32_e32 v82, 0xbfb8aa3b, v82
	v_exp_f32_e32 v82, v82
	s_nop 0
	v_add_f32_e32 v82, v82, v84
	v_cndmask_b32_e32 v82, v83, v82, vcc
	v_mul_f32_e32 v78, v82, v78
	v_cvt_pk_bf16_f32 v78, v78, s0
	ds_write_b16 v103, v78 offset:16384
	v_sub_u32_e32 v78, v112, v114
	v_cvt_f32_u32_e32 v82, v78
	v_cmp_lt_i32_e32 vcc, -1, v78
	v_mul_f32_e32 v82, v82, v131
	v_mul_f32_e32 v82, 0xbfb8aa3b, v82
	v_exp_f32_e32 v82, v82
	s_nop 0
	v_add_f32_e32 v82, 0, v82
	v_cndmask_b32_e32 v83, 0, v82, vcc
	v_cmp_gt_i32_e32 vcc, 1, v78
	v_sub_u32_e32 v78, 0, v78
	v_cvt_f32_u32_e32 v78, v78
	v_mul_f32_e32 v78, v78, v130
	v_mul_f32_e32 v78, 0xbfb8aa3b, v78
	v_exp_f32_e32 v78, v78
	s_nop 0
	v_add_f32_e32 v78, v78, v83
	v_cndmask_b32_e32 v78, v82, v78, vcc
	v_mul_f32_e32 v78, v78, v79
	v_cvt_pk_bf16_f32 v78, v78, s0
	ds_write_b16 v104, v78 offset:16384
	v_sub_u32_e32 v78, v111, v114
	v_cvt_f32_u32_e32 v79, v78
	v_cmp_lt_i32_e32 vcc, -1, v78
	v_mul_f32_e32 v79, v79, v131
	v_mul_f32_e32 v79, 0xbfb8aa3b, v79
	v_exp_f32_e32 v79, v79
	s_nop 0
	v_add_f32_e32 v79, 0, v79
	v_cndmask_b32_e32 v82, 0, v79, vcc
	v_cmp_gt_i32_e32 vcc, 1, v78
	v_sub_u32_e32 v78, 0, v78
	v_cvt_f32_u32_e32 v78, v78
	v_mul_f32_e32 v78, v78, v130
	v_mul_f32_e32 v78, 0xbfb8aa3b, v78
	v_exp_f32_e32 v78, v78
	s_nop 0
	v_add_f32_e32 v78, v78, v82
	v_cndmask_b32_e32 v78, v79, v78, vcc
	v_mul_f32_e32 v78, v78, v80
	v_cvt_pk_bf16_f32 v78, v78, s0
	ds_write_b16 v105, v78 offset:16384
	v_sub_u32_e32 v78, v110, v114
	v_cvt_f32_u32_e32 v79, v78
	v_cmp_lt_i32_e32 vcc, -1, v78
	v_mul_f32_e32 v79, v79, v131
	v_mul_f32_e32 v79, 0xbfb8aa3b, v79
	v_exp_f32_e32 v79, v79
	s_nop 0
	v_add_f32_e32 v79, 0, v79
	v_cndmask_b32_e32 v80, 0, v79, vcc
	v_cmp_gt_i32_e32 vcc, 1, v78
	v_sub_u32_e32 v78, 0, v78
	v_cvt_f32_u32_e32 v78, v78
	v_mul_f32_e32 v78, v78, v130
	v_mul_f32_e32 v78, 0xbfb8aa3b, v78
	v_exp_f32_e32 v78, v78
	s_nop 0
	v_add_f32_e32 v78, v78, v80
	v_cndmask_b32_e32 v78, v79, v78, vcc
	v_mul_f32_e32 v78, v78, v81
	v_cvt_pk_bf16_f32 v78, v78, s0
	ds_write_b16 v107, v78 offset:16384
	v_sub_u32_e32 v78, v115, v113
	v_cvt_f32_u32_e32 v79, v78
	v_cmp_lt_i32_e32 vcc, -1, v78
	v_mul_f32_e32 v79, v79, v131
	v_mul_f32_e32 v79, 0xbfb8aa3b, v79
	v_exp_f32_e32 v79, v79
	s_nop 0
	v_add_f32_e32 v79, 0, v79
	v_cndmask_b32_e32 v80, 0, v79, vcc
	v_cmp_gt_i32_e32 vcc, 1, v78
	v_sub_u32_e32 v78, 0, v78
	v_cvt_f32_u32_e32 v78, v78
	v_mul_f32_e32 v78, v78, v130
	v_mul_f32_e32 v78, 0xbfb8aa3b, v78
	v_exp_f32_e32 v78, v78
	s_nop 0
	v_add_f32_e32 v78, v78, v80
	v_cndmask_b32_e32 v78, v79, v78, vcc
	v_mul_f32_e32 v74, v78, v74
	v_bitop3_b32 v78, v94, 56, v113 bitop3:0x48
	v_lshl_add_u32 v78, v78, 1, 0
	v_cvt_pk_bf16_f32 v74, v74, s0
	v_add3_u32 v78, v78, v98, v137
	ds_write_b16 v78, v74 offset:16384
	v_sub_u32_e32 v74, v112, v113
	v_cvt_f32_u32_e32 v78, v74
	v_cmp_lt_i32_e32 vcc, -1, v74
	v_mul_f32_e32 v78, v78, v131
	v_mul_f32_e32 v78, 0xbfb8aa3b, v78
	v_exp_f32_e32 v78, v78
	s_nop 0
	v_add_f32_e32 v78, 0, v78
	v_cndmask_b32_e32 v79, 0, v78, vcc
	v_cmp_gt_i32_e32 vcc, 1, v74
	v_sub_u32_e32 v74, 0, v74
	v_cvt_f32_u32_e32 v74, v74
	v_mul_f32_e32 v74, v74, v130
	v_mul_f32_e32 v74, 0xbfb8aa3b, v74
	v_exp_f32_e32 v74, v74
	s_nop 0
	v_add_f32_e32 v74, v74, v79
	v_cndmask_b32_e32 v74, v78, v74, vcc
	v_mul_f32_e32 v74, v74, v75
	v_bitop3_b32 v75, v95, 56, v113 bitop3:0x48
	v_lshl_add_u32 v75, v75, 1, 0
	v_cvt_pk_bf16_f32 v74, v74, s0
	v_add3_u32 v75, v75, v99, v137
	ds_write_b16 v75, v74 offset:16384
	v_sub_u32_e32 v74, v111, v113
	v_cvt_f32_u32_e32 v75, v74
	v_cmp_lt_i32_e32 vcc, -1, v74
	v_mul_f32_e32 v75, v75, v131
	v_mul_f32_e32 v75, 0xbfb8aa3b, v75
	v_exp_f32_e32 v75, v75
	s_nop 0
	v_add_f32_e32 v75, 0, v75
	v_cndmask_b32_e32 v78, 0, v75, vcc
	v_cmp_gt_i32_e32 vcc, 1, v74
	v_sub_u32_e32 v74, 0, v74
	v_cvt_f32_u32_e32 v74, v74
	v_mul_f32_e32 v74, v74, v130
	v_mul_f32_e32 v74, 0xbfb8aa3b, v74
	v_exp_f32_e32 v74, v74
	s_nop 0
	v_add_f32_e32 v74, v74, v78
	v_cndmask_b32_e32 v74, v75, v74, vcc
	v_bitop3_b32 v75, v96, 56, v113 bitop3:0x48
	v_mul_f32_e32 v74, v74, v76
	v_lshl_add_u32 v75, v75, 1, 0
	v_cvt_pk_bf16_f32 v74, v74, s0
	v_add3_u32 v75, v75, v100, v137
	ds_write_b16 v75, v74 offset:16384
	v_sub_u32_e32 v74, v110, v113
	v_cvt_f32_u32_e32 v75, v74
	v_cmp_lt_i32_e32 vcc, -1, v74
	v_mul_f32_e32 v75, v75, v131
	v_mul_f32_e32 v75, 0xbfb8aa3b, v75
	v_exp_f32_e32 v75, v75
	s_nop 0
	v_add_f32_e32 v75, 0, v75
	v_cndmask_b32_e32 v76, 0, v75, vcc
	v_cmp_gt_i32_e32 vcc, 1, v74
	v_sub_u32_e32 v74, 0, v74
	v_cvt_f32_u32_e32 v74, v74
	v_mul_f32_e32 v74, v74, v130
	v_mul_f32_e32 v74, 0xbfb8aa3b, v74
	v_exp_f32_e32 v74, v74
	s_nop 0
	v_add_f32_e32 v74, v74, v76
	v_cndmask_b32_e32 v74, v75, v74, vcc
	v_bitop3_b32 v75, v97, 56, v113 bitop3:0x48
	v_mul_f32_e32 v74, v74, v77
	v_lshl_add_u32 v75, v75, 1, 0
	v_cvt_pk_bf16_f32 v74, v74, s0
	v_add3_u32 v75, v75, v101, v137
	ds_write_b16 v75, v74 offset:16384
	v_sub_u32_e32 v74, v115, v106
	v_cvt_f32_u32_e32 v75, v74
	v_cmp_lt_i32_e32 vcc, -1, v74
	v_add3_u32 v113, 0, v135, v134
	v_add_u32_e32 v114, s0, v113
	v_mul_f32_e32 v75, v75, v131
	v_mul_f32_e32 v75, 0xbfb8aa3b, v75
	v_exp_f32_e32 v75, v75
	s_nop 0
	v_add_f32_e32 v75, 0, v75
	v_cndmask_b32_e32 v76, 0, v75, vcc
	v_cmp_gt_i32_e32 vcc, 1, v74
	v_sub_u32_e32 v74, 0, v74
	v_cvt_f32_u32_e32 v74, v74
	v_mul_f32_e32 v74, v74, v130
	v_mul_f32_e32 v74, 0xbfb8aa3b, v74
	v_exp_f32_e32 v74, v74
	s_nop 0
	v_add_f32_e32 v74, v74, v76
	v_cndmask_b32_e32 v74, v75, v74, vcc
	v_mul_f32_e32 v70, v74, v70
	v_bitop3_b32 v74, v94, 56, v106 bitop3:0x48
	v_lshl_add_u32 v74, v74, 1, 0
	v_cvt_pk_bf16_f32 v70, v70, s0
	v_add3_u32 v74, v74, v98, v137
	ds_write_b16 v74, v70 offset:16384
	v_sub_u32_e32 v70, v112, v106
	v_cvt_f32_u32_e32 v74, v70
	v_cmp_lt_i32_e32 vcc, -1, v70
	v_mul_f32_e32 v74, v74, v131
	v_mul_f32_e32 v74, 0xbfb8aa3b, v74
	v_exp_f32_e32 v74, v74
	s_nop 0
	v_add_f32_e32 v74, 0, v74
	v_cndmask_b32_e32 v75, 0, v74, vcc
	v_cmp_gt_i32_e32 vcc, 1, v70
	v_sub_u32_e32 v70, 0, v70
	v_cvt_f32_u32_e32 v70, v70
	v_mul_f32_e32 v70, v70, v130
	v_mul_f32_e32 v70, 0xbfb8aa3b, v70
	v_exp_f32_e32 v70, v70
	s_nop 0
	v_add_f32_e32 v70, v70, v75
	v_cndmask_b32_e32 v70, v74, v70, vcc
	v_mul_f32_e32 v70, v70, v71
	v_bitop3_b32 v71, v95, 56, v106 bitop3:0x48
	v_lshl_add_u32 v71, v71, 1, 0
	v_cvt_pk_bf16_f32 v70, v70, s0
	v_add3_u32 v71, v71, v99, v137
	ds_write_b16 v71, v70 offset:16384
	v_sub_u32_e32 v70, v111, v106
	v_cvt_f32_u32_e32 v71, v70
	v_cmp_lt_i32_e32 vcc, -1, v70
	v_mul_f32_e32 v71, v71, v131
	v_mul_f32_e32 v71, 0xbfb8aa3b, v71
	v_exp_f32_e32 v71, v71
	s_nop 0
	v_add_f32_e32 v71, 0, v71
	v_cndmask_b32_e32 v74, 0, v71, vcc
	v_cmp_gt_i32_e32 vcc, 1, v70
	v_sub_u32_e32 v70, 0, v70
	v_cvt_f32_u32_e32 v70, v70
	v_mul_f32_e32 v70, v70, v130
	v_mul_f32_e32 v70, 0xbfb8aa3b, v70
	v_exp_f32_e32 v70, v70
	s_nop 0
	v_add_f32_e32 v70, v70, v74
	v_cndmask_b32_e32 v70, v71, v70, vcc
	v_bitop3_b32 v71, v96, 56, v106 bitop3:0x48
	v_mul_f32_e32 v70, v70, v72
	v_lshl_add_u32 v71, v71, 1, 0
	v_cvt_pk_bf16_f32 v70, v70, s0
	v_add3_u32 v71, v71, v100, v137
	ds_write_b16 v71, v70 offset:16384
	v_sub_u32_e32 v70, v110, v106
	v_cvt_f32_u32_e32 v71, v70
	v_cmp_lt_i32_e32 vcc, -1, v70
	v_mul_f32_e32 v71, v71, v131
	v_mul_f32_e32 v71, 0xbfb8aa3b, v71
	v_exp_f32_e32 v71, v71
	s_nop 0
	v_add_f32_e32 v71, 0, v71
	v_cndmask_b32_e32 v72, 0, v71, vcc
	v_cmp_gt_i32_e32 vcc, 1, v70
	v_sub_u32_e32 v70, 0, v70
	v_cvt_f32_u32_e32 v70, v70
	v_mul_f32_e32 v70, v70, v130
	v_mul_f32_e32 v70, 0xbfb8aa3b, v70
	v_exp_f32_e32 v70, v70
	s_nop 0
	v_add_f32_e32 v70, v70, v72
	v_cndmask_b32_e32 v70, v71, v70, vcc
	v_bitop3_b32 v71, v97, 56, v106 bitop3:0x48
	v_mul_f32_e32 v70, v70, v73
	v_lshl_add_u32 v71, v71, 1, 0
	v_cvt_pk_bf16_f32 v70, v70, s0
	v_add3_u32 v71, v71, v101, v137
	ds_write_b16 v71, v70 offset:16384
	v_sub_u32_e32 v70, v115, v102
	v_cvt_f32_u32_e32 v71, v70
	v_cmp_lt_i32_e32 vcc, -1, v70
	v_mul_f32_e32 v71, v71, v131
	v_mul_f32_e32 v71, 0xbfb8aa3b, v71
	v_exp_f32_e32 v71, v71
	s_nop 0
	v_add_f32_e32 v71, 0, v71
	v_cndmask_b32_e32 v72, 0, v71, vcc
	v_cmp_gt_i32_e32 vcc, 1, v70
	v_sub_u32_e32 v70, 0, v70
	v_cvt_f32_u32_e32 v70, v70
	v_mul_f32_e32 v70, v70, v130
	v_mul_f32_e32 v70, 0xbfb8aa3b, v70
	v_exp_f32_e32 v70, v70
	s_nop 0
	v_add_f32_e32 v70, v70, v72
	v_cndmask_b32_e32 v70, v71, v70, vcc
	v_mul_f32_e32 v66, v70, v66
	v_bitop3_b32 v70, v94, 56, v102 bitop3:0x48
	v_lshl_add_u32 v70, v70, 1, 0
	v_cvt_pk_bf16_f32 v66, v66, s0
	v_add3_u32 v70, v70, v98, v137
	ds_write_b16 v70, v66 offset:16384
	v_sub_u32_e32 v66, v112, v102
	v_cvt_f32_u32_e32 v70, v66
	v_cmp_lt_i32_e32 vcc, -1, v66
	v_mul_f32_e32 v70, v70, v131
	v_mul_f32_e32 v70, 0xbfb8aa3b, v70
	v_exp_f32_e32 v70, v70
	s_nop 0
	v_add_f32_e32 v70, 0, v70
	v_cndmask_b32_e32 v71, 0, v70, vcc
	v_cmp_gt_i32_e32 vcc, 1, v66
	v_sub_u32_e32 v66, 0, v66
	v_cvt_f32_u32_e32 v66, v66
	v_mul_f32_e32 v66, v66, v130
	v_mul_f32_e32 v66, 0xbfb8aa3b, v66
	v_exp_f32_e32 v66, v66
	s_nop 0
	v_add_f32_e32 v66, v66, v71
	v_cndmask_b32_e32 v66, v70, v66, vcc
	v_mul_f32_e32 v66, v66, v67
	v_bitop3_b32 v67, v95, 56, v102 bitop3:0x48
	v_lshl_add_u32 v67, v67, 1, 0
	v_cvt_pk_bf16_f32 v66, v66, s0
	v_add3_u32 v67, v67, v99, v137
	ds_write_b16 v67, v66 offset:16384
	v_sub_u32_e32 v66, v111, v102
	v_cvt_f32_u32_e32 v67, v66
	v_cmp_lt_i32_e32 vcc, -1, v66
	v_mul_f32_e32 v67, v67, v131
	v_mul_f32_e32 v67, 0xbfb8aa3b, v67
	v_exp_f32_e32 v67, v67
	s_nop 0
	v_add_f32_e32 v67, 0, v67
	v_cndmask_b32_e32 v70, 0, v67, vcc
	v_cmp_gt_i32_e32 vcc, 1, v66
	v_sub_u32_e32 v66, 0, v66
	v_cvt_f32_u32_e32 v66, v66
	v_mul_f32_e32 v66, v66, v130
	v_mul_f32_e32 v66, 0xbfb8aa3b, v66
	v_exp_f32_e32 v66, v66
	s_nop 0
	v_add_f32_e32 v66, v66, v70
	v_cndmask_b32_e32 v66, v67, v66, vcc
	v_bitop3_b32 v67, v96, 56, v102 bitop3:0x48
	v_mul_f32_e32 v66, v66, v68
	v_lshl_add_u32 v67, v67, 1, 0
	v_cvt_pk_bf16_f32 v66, v66, s0
	v_add3_u32 v67, v67, v100, v137
	ds_write_b16 v67, v66 offset:16384
	v_sub_u32_e32 v66, v110, v102
	v_cvt_f32_u32_e32 v67, v66
	v_cmp_lt_i32_e32 vcc, -1, v66
	v_mul_f32_e32 v67, v67, v131
	v_mul_f32_e32 v67, 0xbfb8aa3b, v67
	v_exp_f32_e32 v67, v67
	s_nop 0
	v_add_f32_e32 v67, 0, v67
	v_cndmask_b32_e32 v68, 0, v67, vcc
	v_cmp_gt_i32_e32 vcc, 1, v66
	v_sub_u32_e32 v66, 0, v66
	v_cvt_f32_u32_e32 v66, v66
	v_mul_f32_e32 v66, v66, v130
	v_mul_f32_e32 v66, 0xbfb8aa3b, v66
	v_exp_f32_e32 v66, v66
	s_nop 0
	v_add_f32_e32 v66, v66, v68
	v_cndmask_b32_e32 v66, v67, v66, vcc
	v_bitop3_b32 v67, v97, 56, v102 bitop3:0x48
	v_mul_f32_e32 v66, v66, v69
	v_lshl_add_u32 v67, v67, 1, 0
	v_cvt_pk_bf16_f32 v66, v66, s0
	v_add3_u32 v67, v67, v101, v137
	ds_write_b16 v67, v66 offset:16384
	s_waitcnt lgkmcnt(0)
	s_barrier
	v_and_b32_e32 v232, 15, v207
	v_lshlrev_b32_e32 v232, 1, v232
	v_mov_b32_e32 v233, 0
	v_mov_b32_e32 v247, 0
	v_or_b32_e32 v246, 16, v132
	v_add_u32_e32 v246, s6, v246
	v_mul_u32_u24_e32 v246, 0x1200, v246
	v_lshl_add_u64 v[248:249], s[92:93], 0, v[246:247]
	v_lshl_add_u64 v[248:249], v[248:249], 0, s[26:27]
	v_lshl_add_u64 v[248:249], v[248:249], 0, v[232:233]
	v_lshl_add_u64 v[248:249], v[248:249], 0, s[10:11]
	global_load_ushort v176, v[248:249], off
	global_load_ushort v177, v[248:249], off offset:32
	global_load_ushort v178, v[248:249], off offset:64
	global_load_ushort v179, v[248:249], off offset:96
	v_or_b32_e32 v246, 17, v132
	v_add_u32_e32 v246, s6, v246
	v_mul_u32_u24_e32 v246, 0x1200, v246
	v_lshl_add_u64 v[248:249], s[92:93], 0, v[246:247]
	v_lshl_add_u64 v[248:249], v[248:249], 0, s[26:27]
	v_lshl_add_u64 v[248:249], v[248:249], 0, v[232:233]
	v_lshl_add_u64 v[248:249], v[248:249], 0, s[10:11]
	global_load_ushort v180, v[248:249], off
	global_load_ushort v181, v[248:249], off offset:32
	global_load_ushort v182, v[248:249], off offset:64
	global_load_ushort v183, v[248:249], off offset:96
	v_or_b32_e32 v246, 18, v132
	v_add_u32_e32 v246, s6, v246
	v_mul_u32_u24_e32 v246, 0x1200, v246
	v_lshl_add_u64 v[248:249], s[92:93], 0, v[246:247]
	v_lshl_add_u64 v[248:249], v[248:249], 0, s[26:27]
	v_lshl_add_u64 v[248:249], v[248:249], 0, v[232:233]
	v_lshl_add_u64 v[248:249], v[248:249], 0, s[10:11]
	global_load_ushort v184, v[248:249], off
	global_load_ushort v185, v[248:249], off offset:32
	global_load_ushort v186, v[248:249], off offset:64
	global_load_ushort v187, v[248:249], off offset:96
	v_or_b32_e32 v246, 19, v132
	v_add_u32_e32 v246, s6, v246
	v_mul_u32_u24_e32 v246, 0x1200, v246
	v_lshl_add_u64 v[248:249], s[92:93], 0, v[246:247]
	v_lshl_add_u64 v[248:249], v[248:249], 0, s[26:27]
	v_lshl_add_u64 v[248:249], v[248:249], 0, v[232:233]
	v_lshl_add_u64 v[248:249], v[248:249], 0, s[10:11]
	global_load_ushort v188, v[248:249], off
	global_load_ushort v189, v[248:249], off offset:32
	global_load_ushort v190, v[248:249], off offset:64
	global_load_ushort v191, v[248:249], off offset:96
	ds_read_b128 v[66:69], v114
	ds_read_b128 v[70:73], v114 offset:2048
	ds_read_b128 v[74:77], v113 offset:32768
	ds_read_b128 v[82:85], v113 offset:34816
	ds_read_b128 v[90:93], v113 offset:36864
	ds_read_b128 v[98:101], v113 offset:38912
	s_waitcnt lgkmcnt(3)
	v_mfma_f32_16x16x32_bf16 v[78:81], v[66:69], v[74:77], 0
	v_readlane_b32 s0, v250, 14
	s_add_u32 s4, s0, s26
	v_readlane_b32 s0, v250, 15
	v_mfma_f32_16x16x32_bf16 v[74:77], v[70:73], v[74:77], 0
	s_addc_u32 s5, s0, 0
	s_waitcnt lgkmcnt(2)
	v_mfma_f32_16x16x32_bf16 v[86:89], v[66:69], v[82:85], 0
	v_mfma_f32_16x16x32_bf16 v[82:85], v[70:73], v[82:85], 0
	s_waitcnt lgkmcnt(1)
	v_mfma_f32_16x16x32_bf16 v[94:97], v[66:69], v[90:93], 0
	v_mfma_f32_16x16x32_bf16 v[90:93], v[70:73], v[90:93], 0
	s_waitcnt lgkmcnt(0)
	v_mfma_f32_16x16x32_bf16 v[66:69], v[66:69], v[98:101], 0
	v_mfma_f32_16x16x32_bf16 v[70:73], v[70:73], v[98:101], 0
	ds_read_b128 v[98:101], v125
	ds_read_b128 v[102:105], v125 offset:2048
	ds_read_b128 v[106:109], v124 offset:32768
	s_waitcnt lgkmcnt(0)
	v_mfma_f32_16x16x32_bf16 v[78:81], v[98:101], v[106:109], v[78:81]
	v_mfma_f32_16x16x32_bf16 v[74:77], v[102:105], v[106:109], v[74:77]
	ds_read_b128 v[106:109], v124 offset:34816
	s_waitcnt lgkmcnt(0)
	v_mfma_f32_16x16x32_bf16 v[86:89], v[98:101], v[106:109], v[86:89]
	v_mfma_f32_16x16x32_bf16 v[82:85], v[102:105], v[106:109], v[82:85]
	ds_read_b128 v[106:109], v124 offset:36864
	s_waitcnt lgkmcnt(0)
	v_mfma_f32_16x16x32_bf16 v[94:97], v[98:101], v[106:109], v[94:97]
	v_mfma_f32_16x16x32_bf16 v[90:93], v[102:105], v[106:109], v[90:93]
	ds_read_b128 v[106:109], v124 offset:38912
	s_waitcnt lgkmcnt(0)
	v_mfma_f32_16x16x32_bf16 v[66:69], v[98:101], v[106:109], v[66:69]
	v_mfma_f32_16x16x32_bf16 v[70:73], v[102:105], v[106:109], v[70:73]
	ds_read_b128 v[98:101], v114 offset:16384
	ds_read_b128 v[102:105], v114 offset:18432
	ds_read_b128 v[106:109], v113 offset:40960
	s_waitcnt lgkmcnt(0)
	v_mfma_f32_16x16x32_bf16 v[78:81], v[98:101], v[106:109], v[78:81]
	v_mfma_f32_16x16x32_bf16 v[74:77], v[102:105], v[106:109], v[74:77]
	ds_read_b128 v[106:109], v113 offset:43008
	s_waitcnt lgkmcnt(0)
	v_mfma_f32_16x16x32_bf16 v[86:89], v[98:101], v[106:109], v[86:89]
	v_mfma_f32_16x16x32_bf16 v[106:109], v[102:105], v[106:109], v[82:85]
	s_nop 2
	ds_read_b128 v[82:85], v113 offset:45056
	s_waitcnt lgkmcnt(0)
	v_mfma_f32_16x16x32_bf16 v[116:119], v[98:101], v[82:85], v[94:97]
	v_mfma_f32_16x16x32_bf16 v[120:123], v[102:105], v[82:85], v[90:93]
	ds_read_b128 v[82:85], v113 offset:47104
	s_waitcnt lgkmcnt(0)
	v_mfma_f32_16x16x32_bf16 v[98:101], v[98:101], v[82:85], v[66:69]
	v_mfma_f32_16x16x32_bf16 v[70:73], v[102:105], v[82:85], v[70:73]
	ds_read_b128 v[102:105], v125 offset:16384
	ds_read_b128 v[134:137], v125 offset:18432
	ds_read_b128 v[66:69], v124 offset:40960
	s_waitcnt lgkmcnt(0)
	v_mfma_f32_16x16x32_bf16 v[82:85], v[102:105], v[66:69], v[78:81]
	v_mfma_f32_16x16x32_bf16 v[66:69], v[134:137], v[66:69], v[74:77]
	s_nop 2
	ds_read_b128 v[74:77], v124 offset:43008
	s_waitcnt lgkmcnt(0)
	v_mfma_f32_16x16x32_bf16 v[78:81], v[134:137], v[74:77], v[106:109]
	s_nop 2
	ds_read_b128 v[106:109], v124 offset:47104
	v_mfma_f32_16x16x32_bf16 v[94:97], v[102:105], v[74:77], v[86:89]
	ds_read_b128 v[74:77], v124 offset:45056
	s_waitcnt lgkmcnt(1)
	v_mfma_f32_16x16x32_bf16 v[86:89], v[102:105], v[106:109], v[98:101]
	s_nop 2
	v_and_b32_e32 v99, 64, v207
	v_xor_b32_e32 v98, 1, v207
	v_add_u32_e32 v99, 64, v99
	v_cmp_lt_i32_e32 vcc, v98, v99
	s_waitcnt lgkmcnt(0)
	v_mfma_f32_16x16x32_bf16 v[90:93], v[102:105], v[74:77], v[116:119]
	v_mov_b32_e32 v100, v38
	v_cndmask_b32_e32 v98, v207, v98, vcc
	v_mov_b32_e32 v101, v34
	v_lshlrev_b32_e32 v117, 2, v98
	v_xor_b32_e32 v98, 2, v207
	v_cmp_lt_i32_e32 vcc, v98, v99
	v_mov_b32_e32 v102, v46
	v_mov_b32_e32 v103, v42
	v_cndmask_b32_e32 v98, v207, v98, vcc
	v_lshlrev_b32_e32 v116, 2, v98
	v_xor_b32_e32 v98, 4, v207
	v_cmp_lt_i32_e32 vcc, v98, v99
	v_mfma_f32_16x16x32_bf16 v[70:73], v[134:137], v[106:109], v[70:73]
	v_mov_b32_e32 v107, v62
	v_cndmask_b32_e32 v98, v207, v98, vcc
	v_lshlrev_b32_e32 v114, 2, v98
	v_xor_b32_e32 v98, 8, v207
	v_cmp_lt_i32_e32 vcc, v98, v99
	v_mov_b32_e32 v105, v86
	v_mfma_f32_16x16x32_bf16 v[74:77], v[134:137], v[74:77], v[120:123]
	v_cndmask_b32_e32 v98, v207, v98, vcc
	v_lshlrev_b32_e32 v113, 2, v98
	v_cvt_f32_i32_e32 v98, v133
	v_mul_f32_e32 v98, v98, v131
	v_mul_f32_e32 v98, 0xbfb8aa3b, v98
	v_exp_f32_e32 v99, v98
	v_sub_u32_e32 v98, 0x80, v132
	v_cvt_f32_i32_e32 v98, v98
	v_mul_f32_e32 v98, v98, v130
	v_mul_f32_e32 v98, 0xbfb8aa3b, v98
	v_exp_f32_e32 v98, v98
	s_nop 0
	v_pk_mul_f32 v[100:101], v[98:99], v[100:101]
	s_nop 0
	v_add_f32_e32 v34, v101, v82
	v_pk_mul_f32 v[102:103], v[98:99], v[102:103]
	v_add_f32_e32 v100, v100, v34
	v_add_f32_e32 v34, v103, v94
	v_add_f32_e32 v46, v102, v34
	v_mov_b32_e32 v102, v54
	v_mov_b32_e32 v103, v50
	v_pk_mul_f32 v[102:103], v[98:99], v[102:103]
	v_mul_f32_e32 v104, v46, v46
	v_add_f32_e32 v34, v103, v90
	v_add_f32_e32 v102, v102, v34
	v_mov_b32_e32 v101, v99
	v_mov_b32_e32 v106, v100
	v_pk_fma_f32 v[104:105], v[100:101], v[106:107], v[104:105]
	v_mov_b32_e32 v103, v98
	v_mov_b32_e32 v98, v102
	v_mov_b32_e32 v99, v58
	v_pk_fma_f32 v[104:105], v[102:103], v[98:99], v[104:105]
	v_add_u32_e32 v106, s6, v132
	v_mov_b64_e32 v[98:99], s[92:93]
	v_mad_i64_i32 v[108:109], s[0:1], v106, s3, v[98:99]
	v_lshl_add_u64 v[108:109], v[108:109], 0, s[26:27]
	v_lshl_add_u64 v[118:119], v[108:109], 0, v[0:1]
	v_lshl_add_u64 v[108:109], v[118:119], 0, s[10:11]
	v_add_co_u32_e32 v118, vcc, s7, v118
	v_ashrrev_i32_e32 v107, 31, v106
	s_nop 0
	v_addc_co_u32_e32 v119, vcc, 0, v119, vcc
	v_lshlrev_b64 v[106:107], 11, v[106:107]
	v_lshl_add_u64 v[106:107], s[4:5], 0, v[106:107]
	v_lshl_add_u64 v[106:107], v[106:107], 0, v[0:1]
	s_waitcnt vmcnt(16)
	v_lshlrev_b32_e32 v34, 16, v216
	v_mul_f32_e32 v38, 0xbfb8aa3b, v34
	v_exp_f32_e32 v38, v38
	s_nop 0
	v_add_f32_e32 v38, 1.0, v38
	v_div_scale_f32 v42, s[0:1], v38, v38, v34
	v_rcp_f32_e32 v50, v42
	s_nop 0
	v_fma_f32 v54, -v42, v50, 1.0
	v_fmac_f32_e32 v50, v54, v50
	v_div_scale_f32 v54, vcc, v34, v38, v34
	v_mul_f32_e32 v58, v54, v50
	v_fma_f32 v62, -v42, v58, v54
	v_fmac_f32_e32 v58, v62, v50
	v_fma_f32 v42, -v42, v58, v54
	v_div_fmas_f32 v42, v42, v50, v58
	v_div_fixup_f32 v82, v42, v38, v34
	s_nop 0
	v_lshlrev_b32_e32 v34, 16, v217
	v_mul_f32_e32 v38, 0xbfb8aa3b, v34
	v_exp_f32_e32 v38, v38
	s_nop 0
	v_add_f32_e32 v38, 1.0, v38
	v_div_scale_f32 v42, s[0:1], v38, v38, v34
	v_rcp_f32_e32 v50, v42
	s_nop 0
	v_fma_f32 v54, -v42, v50, 1.0
	v_fmac_f32_e32 v50, v54, v50
	v_div_scale_f32 v54, vcc, v34, v38, v34
	v_mul_f32_e32 v58, v54, v50
	v_fma_f32 v62, -v42, v58, v54
	v_fmac_f32_e32 v58, v62, v50
	v_fma_f32 v42, -v42, v58, v54
	v_div_fmas_f32 v42, v42, v50, v58
	v_div_fixup_f32 v90, v42, v38, v34
	s_nop 0
	v_lshlrev_b32_e32 v34, 16, v218
	v_mul_f32_e32 v38, 0xbfb8aa3b, v34
	v_exp_f32_e32 v38, v38
	s_nop 0
	v_add_f32_e32 v38, 1.0, v38
	v_div_scale_f32 v42, s[0:1], v38, v38, v34
	v_rcp_f32_e32 v50, v42
	s_nop 0
	v_fma_f32 v54, -v42, v50, 1.0
	v_fmac_f32_e32 v50, v54, v50
	v_div_scale_f32 v54, vcc, v34, v38, v34
	v_mul_f32_e32 v58, v54, v50
	v_fma_f32 v62, -v42, v58, v54
	v_fmac_f32_e32 v58, v62, v50
	v_fma_f32 v42, -v42, v58, v54
	v_div_fmas_f32 v42, v42, v50, v58
	v_div_fixup_f32 v94, v42, v38, v34
	s_nop 0
	v_lshlrev_b32_e32 v34, 16, v219
	v_mul_f32_e32 v38, 0xbfb8aa3b, v34
	v_exp_f32_e32 v38, v38
	s_nop 0
	v_add_f32_e32 v38, 1.0, v38
	v_div_scale_f32 v42, s[0:1], v38, v38, v34
	v_rcp_f32_e32 v50, v42
	s_mov_b32 s0, 0x358637bd
	v_fma_f32 v54, -v42, v50, 1.0
	v_fmac_f32_e32 v50, v54, v50
	v_div_scale_f32 v54, vcc, v34, v38, v34
	v_mul_f32_e32 v58, v54, v50
	v_fma_f32 v62, -v42, v58, v54
	v_fmac_f32_e32 v58, v62, v50
	v_fma_f32 v42, -v42, v58, v54
	v_div_fmas_f32 v42, v42, v50, v58
	v_div_fixup_f32 v101, v42, v38, v34
	v_cvt_f32_i32_e32 v34, v127
	v_mov_b32_e32 v42, v47
	v_mov_b32_e32 v50, v55
	v_mul_f32_e32 v34, v34, v131
	v_mul_f32_e32 v34, 0xbfb8aa3b, v34
	v_exp_f32_e32 v109, v34
	v_sub_u32_e32 v34, 0x80, v133
	v_cvt_f32_i32_e32 v34, v34
	v_mov_b32_e32 v55, v109
	v_mul_f32_e32 v34, v34, v130
	v_mul_f32_e32 v34, 0xbfb8aa3b, v34
	v_exp_f32_e32 v108, v34
	v_mov_b32_e32 v34, v39
	v_pk_mul_f32 v[34:35], v[108:109], v[34:35]
	s_nop 0
	v_add_f32_e32 v35, v35, v83
	v_add_f32_e32 v54, v34, v35
	v_pk_mul_f32 v[34:35], v[108:109], v[42:43]
	v_mov_b32_e32 v62, v54
	v_add_f32_e32 v35, v35, v95
	v_add_f32_e32 v83, v34, v35
	v_pk_mul_f32 v[34:35], v[108:109], v[50:51]
	v_mul_f32_e32 v86, v83, v83
	v_add_f32_e32 v35, v35, v91
	v_add_f32_e32 v42, v34, v35
	v_pk_fma_f32 v[34:35], v[54:55], v[62:63], v[86:87]
	v_mov_b32_e32 v43, v108
	v_mov_b32_e32 v58, v42
	v_pk_fma_f32 v[38:39], v[42:43], v[58:59], v[34:35]
	v_mov_b32_e32 v35, v105
	v_mov_b32_e32 v34, v39
	v_mov_b32_e32 v50, v38
	v_mov_b32_e32 v51, v104
	v_pk_fma_f32 v[34:35], v[34:35], v[34:35], v[50:51]
	s_nop 1
	v_add_f32_dpp v34, v34, v34 quad_perm:[1,0,3,2] row_mask:0xf bank_mask:0xf
	v_add_f32_dpp v35, v35, v35 quad_perm:[1,0,3,2] row_mask:0xf bank_mask:0xf
	s_nop 0
	v_add_f32_dpp v34, v34, v34 quad_perm:[2,3,0,1] row_mask:0xf bank_mask:0xf
	v_add_f32_dpp v35, v35, v35 quad_perm:[2,3,0,1] row_mask:0xf bank_mask:0xf
	s_nop 0
	v_add_f32_dpp v34, v34, v34 row_half_mirror row_mask:0xf bank_mask:0xf
	v_add_f32_dpp v35, v35, v35 row_half_mirror row_mask:0xf bank_mask:0xf
	s_nop 0
	v_add_f32_dpp v34, v34, v34 row_mirror row_mask:0xf bank_mask:0xf
	v_add_f32_dpp v35, v35, v35 row_mirror row_mask:0xf bank_mask:0xf
	s_nop 0
	v_mov_b32_e32 v50, v34
	v_mov_b32_e32 v51, v35
	v_mov_b64_e32 v[34:35], s[0:1]
	v_pk_fma_f32 v[50:51], v[50:51], s[12:13], v[34:35] op_sel_hi:[1,0,0]
	s_nop 0
	v_mul_f32_e32 v38, 0x4b800000, v51
	v_cmp_gt_f32_e64 s[0:1], s8, v51
	v_cmp_gt_f32_e32 vcc, s8, v50
	s_nop 0
	v_cndmask_b32_e64 v38, v51, v38, s[0:1]
	v_rsq_f32_e32 v38, v38
	s_nop 0
	v_mul_f32_e32 v43, 0x45800000, v38
	v_cndmask_b32_e64 v38, v38, v43, s[0:1]
	v_mul_f32_e32 v43, v100, v38
	v_mul_f32_e32 v43, v82, v43
	v_cvt_pk_bf16_f32 v43, v43, s0
	global_store_short v[106:107], v43, off
	v_mul_f32_e32 v43, v46, v38
	v_mul_f32_e32 v43, v43, v90
	v_cvt_pk_bf16_f32 v43, v43, s0
	global_store_short v[106:107], v43, off offset:32
	v_mul_f32_e32 v43, v102, v38
	v_mul_f32_e32 v38, v105, v38
	v_mul_f32_e32 v38, v38, v101
	v_cvt_pk_bf16_f32 v38, v38, s0
	global_store_short v[106:107], v38, off offset:96
	v_mul_f32_e32 v38, 0x4b800000, v50
	v_cndmask_b32_e32 v38, v50, v38, vcc
	v_rsq_f32_e32 v38, v38
	v_mul_f32_e32 v43, v43, v94
	v_add_u32_e32 v46, s6, v133
	v_cvt_pk_bf16_f32 v43, v43, s0
	v_mad_i64_i32 v[50:51], s[0:1], v46, s3, v[98:99]
	v_ashrrev_i32_e32 v47, 31, v46
	v_lshl_add_u64 v[50:51], v[50:51], 0, s[26:27]
	global_store_short v[106:107], v43, off offset:64
	v_mul_f32_e32 v43, 0x45800000, v38
	v_lshlrev_b64 v[46:47], 11, v[46:47]
	v_lshl_add_u64 v[50:51], v[50:51], 0, v[0:1]
	v_cndmask_b32_e32 v38, v38, v43, vcc
	v_lshl_add_u64 v[58:59], s[4:5], 0, v[46:47]
	v_lshl_add_u64 v[46:47], v[50:51], 0, s[10:11]
	v_add_co_u32_e32 v50, vcc, s7, v50
	v_mul_f32_e32 v42, v42, v38
	s_nop 0
	v_addc_co_u32_e32 v51, vcc, 0, v51, vcc
	v_mul_f32_e32 v50, v54, v38
	s_nop 0
	v_lshlrev_b32_e32 v43, 16, v220
	v_mul_f32_e32 v51, 0xbfb8aa3b, v43
	v_exp_f32_e32 v51, v51
	s_nop 0
	v_add_f32_e32 v51, 1.0, v51
	v_div_scale_f32 v54, s[0:1], v51, v51, v43
	v_rcp_f32_e32 v55, v54
	s_nop 0
	v_fma_f32 v62, -v54, v55, 1.0
	v_fmac_f32_e32 v55, v62, v55
	v_div_scale_f32 v62, vcc, v43, v51, v43
	v_mul_f32_e32 v63, v62, v55
	v_fma_f32 v82, -v54, v63, v62
	v_fmac_f32_e32 v63, v82, v55
	v_fma_f32 v54, -v54, v63, v62
	v_div_fmas_f32 v54, v54, v55, v63
	v_div_fixup_f32 v43, v54, v51, v43
	v_mul_f32_e32 v43, v43, v50
	v_cvt_pk_bf16_f32 v43, v43, s0
	v_lshl_add_u64 v[50:51], v[58:59], 0, v[0:1]
	global_store_short v[50:51], v43, off
	v_mul_f32_e32 v54, v83, v38
	v_mul_f32_e32 v38, v39, v38
	s_nop 0
	v_lshlrev_b32_e32 v43, 16, v221
	v_mul_f32_e32 v55, 0xbfb8aa3b, v43
	v_exp_f32_e32 v55, v55
	s_nop 0
	v_add_f32_e32 v55, 1.0, v55
	v_div_scale_f32 v58, s[0:1], v55, v55, v43
	v_rcp_f32_e32 v59, v58
	s_nop 0
	v_fma_f32 v62, -v58, v59, 1.0
	v_fmac_f32_e32 v59, v62, v59
	v_div_scale_f32 v62, vcc, v43, v55, v43
	v_mul_f32_e32 v63, v62, v59
	v_fma_f32 v82, -v58, v63, v62
	v_fmac_f32_e32 v63, v82, v59
	v_fma_f32 v58, -v58, v63, v62
	v_div_fmas_f32 v58, v58, v59, v63
	v_div_fixup_f32 v43, v58, v55, v43
	v_mul_f32_e32 v43, v54, v43
	v_cvt_pk_bf16_f32 v43, v43, s0
	global_store_short v[50:51], v43, off offset:32
	s_nop 0
	v_lshlrev_b32_e32 v43, 16, v222
	v_mul_f32_e32 v54, 0xbfb8aa3b, v43
	v_exp_f32_e32 v54, v54
	s_nop 0
	v_add_f32_e32 v54, 1.0, v54
	v_div_scale_f32 v55, s[0:1], v54, v54, v43
	v_rcp_f32_e32 v58, v55
	s_nop 0
	v_fma_f32 v59, -v55, v58, 1.0
	v_fmac_f32_e32 v58, v59, v58
	v_div_scale_f32 v59, vcc, v43, v54, v43
	v_mul_f32_e32 v62, v59, v58
	v_fma_f32 v63, -v55, v62, v59
	v_fmac_f32_e32 v62, v63, v58
	v_fma_f32 v55, -v55, v62, v59
	v_div_fmas_f32 v55, v55, v58, v62
	v_div_fixup_f32 v43, v55, v54, v43
	v_mul_f32_e32 v42, v42, v43
	v_cvt_pk_bf16_f32 v42, v42, s0
	global_store_short v[50:51], v42, off offset:64
	s_nop 0
	v_lshlrev_b32_e32 v42, 16, v223
	v_mul_f32_e32 v39, 0xbfb8aa3b, v42
	v_exp_f32_e32 v39, v39
	s_nop 0
	v_add_f32_e32 v39, 1.0, v39
	v_div_scale_f32 v43, s[0:1], v39, v39, v42
	v_rcp_f32_e32 v46, v43
	s_nop 0
	v_fma_f32 v47, -v43, v46, 1.0
	v_fmac_f32_e32 v46, v47, v46
	v_div_scale_f32 v47, vcc, v42, v39, v42
	v_mul_f32_e32 v54, v47, v46
	v_fma_f32 v55, -v43, v54, v47
	v_fmac_f32_e32 v54, v55, v46
	v_fma_f32 v43, -v43, v54, v47
	v_div_fmas_f32 v43, v43, v46, v54
	v_div_fixup_f32 v39, v43, v39, v42
	v_mul_f32_e32 v38, v38, v39
	v_cvt_pk_bf16_f32 v38, v38, s0
	global_store_short v[50:51], v38, off offset:96
	v_cvt_f32_i32_e32 v38, v126
	v_mov_b32_e32 v39, v36
	v_mov_b32_e32 v42, v48
	v_mov_b32_e32 v43, v44
	v_mul_f32_e32 v38, v38, v131
	v_mul_f32_e32 v38, 0xbfb8aa3b, v38
	v_exp_f32_e32 v47, v38
	v_sub_u32_e32 v38, 0x80, v127
	v_cvt_f32_i32_e32 v38, v38
	v_mov_b32_e32 v55, v64
	v_mov_b32_e32 v51, v88
	v_mul_f32_e32 v38, v38, v130
	v_mul_f32_e32 v38, 0xbfb8aa3b, v38
	v_exp_f32_e32 v46, v38
	v_mov_b32_e32 v38, v40
	v_pk_mul_f32 v[38:39], v[46:47], v[38:39]
	s_nop 0
	v_add_f32_e32 v36, v39, v84
	v_pk_mul_f32 v[42:43], v[46:47], v[42:43]
	v_add_f32_e32 v38, v38, v36
	v_add_f32_e32 v36, v43, v96
	v_add_f32_e32 v58, v42, v36
	v_mov_b32_e32 v42, v56
	v_mov_b32_e32 v43, v52
	v_pk_mul_f32 v[42:43], v[46:47], v[42:43]
	v_mul_f32_e32 v50, v58, v58
	v_add_f32_e32 v36, v43, v92
	v_add_f32_e32 v42, v42, v36
	v_mov_b32_e32 v39, v47
	v_mov_b32_e32 v54, v38
	v_pk_fma_f32 v[50:51], v[38:39], v[54:55], v[50:51]
	v_mov_b32_e32 v43, v46
	v_mov_b32_e32 v46, v42
	v_mov_b32_e32 v47, v60
	v_pk_fma_f32 v[46:47], v[42:43], v[46:47], v[50:51]
	v_add_u32_e32 v50, s6, v127
	v_mad_i64_i32 v[54:55], s[0:1], v50, s3, v[98:99]
	v_lshl_add_u64 v[54:55], v[54:55], 0, s[26:27]
	v_lshl_add_u64 v[62:63], v[54:55], 0, v[0:1]
	v_lshl_add_u64 v[54:55], v[62:63], 0, s[10:11]
	v_add_co_u32_e32 v62, vcc, s7, v62
	v_ashrrev_i32_e32 v51, 31, v50
	s_nop 0
	v_addc_co_u32_e32 v63, vcc, 0, v63, vcc
	v_lshlrev_b64 v[50:51], 11, v[50:51]
	v_lshl_add_u64 v[50:51], s[4:5], 0, v[50:51]
	v_lshl_add_u64 v[50:51], v[50:51], 0, v[0:1]
	s_nop 0
	v_lshlrev_b32_e32 v36, 16, v224
	v_mul_f32_e32 v39, 0xbfb8aa3b, v36
	v_exp_f32_e32 v39, v39
	s_nop 0
	v_add_f32_e32 v39, 1.0, v39
	v_div_scale_f32 v40, s[0:1], v39, v39, v36
	v_rcp_f32_e32 v43, v40
	s_nop 0
	v_fma_f32 v44, -v40, v43, 1.0
	v_fmac_f32_e32 v43, v44, v43
	v_div_scale_f32 v44, vcc, v36, v39, v36
	v_mul_f32_e32 v48, v44, v43
	v_fma_f32 v52, -v40, v48, v44
	v_fmac_f32_e32 v48, v52, v43
	v_fma_f32 v40, -v40, v48, v44
	v_div_fmas_f32 v40, v40, v43, v48
	v_div_fixup_f32 v39, v40, v39, v36
	s_nop 0
	v_lshlrev_b32_e32 v36, 16, v225
	v_mul_f32_e32 v40, 0xbfb8aa3b, v36
	v_exp_f32_e32 v40, v40
	s_nop 0
	v_add_f32_e32 v40, 1.0, v40
	v_div_scale_f32 v43, s[0:1], v40, v40, v36
	v_rcp_f32_e32 v44, v43
	s_nop 0
	v_fma_f32 v48, -v43, v44, 1.0
	v_fmac_f32_e32 v44, v48, v44
	v_div_scale_f32 v48, vcc, v36, v40, v36
	v_mul_f32_e32 v52, v48, v44
	v_fma_f32 v56, -v43, v52, v48
	v_fmac_f32_e32 v52, v56, v44
	v_fma_f32 v43, -v43, v52, v48
	v_div_fmas_f32 v43, v43, v44, v52
	v_div_fixup_f32 v43, v43, v40, v36
	s_nop 0
	v_lshlrev_b32_e32 v36, 16, v226
	v_mul_f32_e32 v40, 0xbfb8aa3b, v36
	v_exp_f32_e32 v40, v40
	s_nop 0
	v_add_f32_e32 v40, 1.0, v40
	v_div_scale_f32 v44, s[0:1], v40, v40, v36
	v_rcp_f32_e32 v48, v44
	s_nop 0
	v_fma_f32 v52, -v44, v48, 1.0
	v_fmac_f32_e32 v48, v52, v48
	v_div_scale_f32 v52, vcc, v36, v40, v36
	v_mul_f32_e32 v56, v52, v48
	v_fma_f32 v59, -v44, v56, v52
	v_fmac_f32_e32 v56, v59, v48
	v_fma_f32 v44, -v44, v56, v52
	v_div_fmas_f32 v44, v44, v48, v56
	v_div_fixup_f32 v56, v44, v40, v36
	s_nop 0
	v_lshlrev_b32_e32 v36, 16, v227
	v_mul_f32_e32 v40, 0xbfb8aa3b, v36
	v_exp_f32_e32 v40, v40
	s_nop 0
	v_add_f32_e32 v40, 1.0, v40
	v_div_scale_f32 v44, s[0:1], v40, v40, v36
	v_rcp_f32_e32 v48, v44
	s_nop 0
	v_fma_f32 v52, -v44, v48, 1.0
	v_fmac_f32_e32 v48, v52, v48
	v_div_scale_f32 v52, vcc, v36, v40, v36
	v_mul_f32_e32 v54, v52, v48
	v_fma_f32 v55, -v44, v54, v52
	v_fmac_f32_e32 v54, v55, v48
	v_fma_f32 v44, -v44, v54, v52
	v_div_fmas_f32 v44, v44, v48, v54
	v_div_fixup_f32 v59, v44, v40, v36
	v_add_u32_e32 v36, 4, v132
	v_cvt_f32_i32_e32 v36, v36
	v_mov_b32_e32 v44, v49
	v_mov_b32_e32 v52, v57
	v_mul_f32_e32 v36, v36, v131
	v_mul_f32_e32 v36, 0xbfb8aa3b, v36
	v_exp_f32_e32 v55, v36
	v_sub_u32_e32 v36, 0x80, v126
	v_cvt_f32_i32_e32 v36, v36
	v_mov_b32_e32 v49, v55
	v_mul_f32_e32 v36, v36, v130
	v_mul_f32_e32 v36, 0xbfb8aa3b, v36
	v_exp_f32_e32 v54, v36
	v_mov_b32_e32 v36, v41
	v_pk_mul_f32 v[36:37], v[54:55], v[36:37]
	s_nop 0
	v_add_f32_e32 v37, v37, v85
	v_add_f32_e32 v48, v36, v37
	v_pk_mul_f32 v[36:37], v[54:55], v[44:45]
	v_mov_b32_e32 v64, v48
	v_add_f32_e32 v37, v37, v97
	v_add_f32_e32 v62, v36, v37
	v_pk_mul_f32 v[36:37], v[54:55], v[52:53]
	v_mul_f32_e32 v88, v62, v62
	v_add_f32_e32 v37, v37, v93
	v_add_f32_e32 v40, v36, v37
	v_pk_fma_f32 v[36:37], v[48:49], v[64:65], v[88:89]
	v_mov_b32_e32 v41, v54
	v_mov_b32_e32 v60, v40
	v_pk_fma_f32 v[36:37], v[40:41], v[60:61], v[36:37]
	v_mov_b32_e32 v45, v47
	v_mov_b32_e32 v44, v37
	v_mov_b32_e32 v52, v36
	v_mov_b32_e32 v53, v46
	v_pk_fma_f32 v[44:45], v[44:45], v[44:45], v[52:53]
	s_nop 1
	v_add_f32_dpp v44, v44, v44 quad_perm:[1,0,3,2] row_mask:0xf bank_mask:0xf
	v_add_f32_dpp v45, v45, v45 quad_perm:[1,0,3,2] row_mask:0xf bank_mask:0xf
	s_nop 0
	v_add_f32_dpp v44, v44, v44 quad_perm:[2,3,0,1] row_mask:0xf bank_mask:0xf
	v_add_f32_dpp v45, v45, v45 quad_perm:[2,3,0,1] row_mask:0xf bank_mask:0xf
	s_nop 0
	v_add_f32_dpp v44, v44, v44 row_half_mirror row_mask:0xf bank_mask:0xf
	v_add_f32_dpp v45, v45, v45 row_half_mirror row_mask:0xf bank_mask:0xf
	s_nop 0
	v_add_f32_dpp v44, v44, v44 row_mirror row_mask:0xf bank_mask:0xf
	v_add_f32_dpp v45, v45, v45 row_mirror row_mask:0xf bank_mask:0xf
	s_nop 0
	s_nop 0
	v_pk_fma_f32 v[44:45], v[44:45], s[12:13], v[34:35] op_sel_hi:[1,0,0]
	s_nop 0
	v_mul_f32_e32 v36, 0x4b800000, v45
	v_cmp_gt_f32_e64 s[0:1], s8, v45
	v_cmp_gt_f32_e32 vcc, s8, v44
	s_nop 0
	v_cndmask_b32_e64 v36, v45, v36, s[0:1]
	v_rsq_f32_e32 v36, v36
	s_nop 0
	v_mul_f32_e32 v41, 0x45800000, v36
	v_cndmask_b32_e64 v36, v36, v41, s[0:1]
	v_mul_f32_e32 v38, v38, v36
	v_mul_f32_e32 v38, v39, v38
	v_cvt_pk_bf16_f32 v38, v38, s0
	global_store_short v[50:51], v38, off
	v_mul_f32_e32 v38, v58, v36
	v_mul_f32_e32 v38, v38, v43
	v_cvt_pk_bf16_f32 v38, v38, s0
	global_store_short v[50:51], v38, off offset:32
	v_mul_f32_e32 v38, v42, v36
	v_mul_f32_e32 v36, v47, v36
	v_mul_f32_e32 v36, v36, v59
	v_cvt_pk_bf16_f32 v36, v36, s0
	global_store_short v[50:51], v36, off offset:96
	v_mul_f32_e32 v36, 0x4b800000, v44
	v_cndmask_b32_e32 v36, v44, v36, vcc
	v_rsq_f32_e32 v36, v36
	v_mul_f32_e32 v38, v38, v56
	v_cvt_pk_bf16_f32 v38, v38, s0
	global_store_short v[50:51], v38, off offset:64
	v_mul_f32_e32 v38, 0x45800000, v36
	v_cndmask_b32_e32 v36, v36, v38, vcc
	v_add_u32_e32 v38, s6, v126
	v_mad_i64_i32 v[42:43], s[0:1], v38, s3, v[98:99]
	v_ashrrev_i32_e32 v39, 31, v38
	v_lshl_add_u64 v[42:43], v[42:43], 0, s[26:27]
	v_lshlrev_b64 v[38:39], 11, v[38:39]
	v_lshl_add_u64 v[42:43], v[42:43], 0, v[0:1]
	v_lshl_add_u64 v[44:45], s[4:5], 0, v[38:39]
	v_lshl_add_u64 v[38:39], v[42:43], 0, s[10:11]
	v_add_co_u32_e32 v42, vcc, s7, v42
	v_mul_f32_e32 v40, v40, v36
	s_nop 0
	v_addc_co_u32_e32 v43, vcc, 0, v43, vcc
	v_mul_f32_e32 v42, v48, v36
	s_nop 0
	v_lshlrev_b32_e32 v41, 16, v228
	v_mul_f32_e32 v43, 0xbfb8aa3b, v41
	v_exp_f32_e32 v43, v43
	s_nop 0
	v_add_f32_e32 v43, 1.0, v43
	v_div_scale_f32 v46, s[0:1], v43, v43, v41
	v_rcp_f32_e32 v47, v46
	s_nop 0
	v_fma_f32 v48, -v46, v47, 1.0
	v_fmac_f32_e32 v47, v48, v47
	v_div_scale_f32 v48, vcc, v41, v43, v41
	v_mul_f32_e32 v49, v48, v47
	v_fma_f32 v50, -v46, v49, v48
	v_fmac_f32_e32 v49, v50, v47
	v_fma_f32 v46, -v46, v49, v48
	v_div_fmas_f32 v46, v46, v47, v49
	v_div_fixup_f32 v41, v46, v43, v41
	v_mul_f32_e32 v41, v41, v42
	v_cvt_pk_bf16_f32 v41, v41, s0
	v_lshl_add_u64 v[42:43], v[44:45], 0, v[0:1]
	global_store_short v[42:43], v41, off
	v_mul_f32_e32 v44, v62, v36
	v_mul_f32_e32 v36, v37, v36
	s_nop 0
	v_lshlrev_b32_e32 v41, 16, v229
	v_mul_f32_e32 v45, 0xbfb8aa3b, v41
	v_exp_f32_e32 v45, v45
	s_nop 0
	v_add_f32_e32 v45, 1.0, v45
	v_div_scale_f32 v46, s[0:1], v45, v45, v41
	v_rcp_f32_e32 v47, v46
	s_nop 0
	v_fma_f32 v48, -v46, v47, 1.0
	v_fmac_f32_e32 v47, v48, v47
	v_div_scale_f32 v48, vcc, v41, v45, v41
	v_mul_f32_e32 v49, v48, v47
	v_fma_f32 v50, -v46, v49, v48
	v_fmac_f32_e32 v49, v50, v47
	v_fma_f32 v46, -v46, v49, v48
	v_div_fmas_f32 v46, v46, v47, v49
	v_div_fixup_f32 v41, v46, v45, v41
	v_mul_f32_e32 v41, v44, v41
	v_cvt_pk_bf16_f32 v41, v41, s0
	global_store_short v[42:43], v41, off offset:32
	s_nop 0
	v_lshlrev_b32_e32 v41, 16, v230
	v_mul_f32_e32 v44, 0xbfb8aa3b, v41
	v_exp_f32_e32 v44, v44
	s_nop 0
	v_lshlrev_b32_e32 v38, 16, v231
	v_add_f32_e32 v44, 1.0, v44
	v_div_scale_f32 v45, s[0:1], v44, v44, v41
	v_rcp_f32_e32 v46, v45
	v_mul_f32_e32 v37, 0xbfb8aa3b, v38
	v_exp_f32_e32 v37, v37
	v_fma_f32 v47, -v45, v46, 1.0
	v_fmac_f32_e32 v46, v47, v46
	v_div_scale_f32 v47, vcc, v41, v44, v41
	v_mul_f32_e32 v48, v47, v46
	v_fma_f32 v49, -v45, v48, v47
	v_fmac_f32_e32 v48, v49, v46
	v_fma_f32 v45, -v45, v48, v47
	v_div_fmas_f32 v45, v45, v46, v48
	v_div_fixup_f32 v41, v45, v44, v41
	v_mul_f32_e32 v40, v40, v41
	v_add_f32_e32 v37, 1.0, v37
	v_cvt_pk_bf16_f32 v40, v40, s0
	v_div_scale_f32 v39, s[0:1], v37, v37, v38
	global_store_short v[42:43], v40, off offset:64
	v_rcp_f32_e32 v40, v39
	s_nop 0
	v_fma_f32 v41, -v39, v40, 1.0
	v_fmac_f32_e32 v40, v41, v40
	v_div_scale_f32 v41, vcc, v38, v37, v38
	v_mul_f32_e32 v44, v41, v40
	v_fma_f32 v45, -v39, v44, v41
	v_fmac_f32_e32 v44, v45, v40
	v_fma_f32 v39, -v39, v44, v41
	v_div_fmas_f32 v39, v39, v40, v44
	v_div_fixup_f32 v37, v39, v37, v38
	v_mul_f32_e32 v36, v36, v37
	v_cvt_pk_bf16_f32 v36, v36, s0
	global_store_short v[42:43], v36, off offset:96
	v_cvt_f32_i32_e32 v36, v112
	v_mov_b32_e32 v37, v2
	v_mov_b32_e32 v38, v14
	v_mov_b32_e32 v39, v10
	v_mul_f32_e32 v36, v36, v131
	v_mul_f32_e32 v36, 0xbfb8aa3b, v36
	v_exp_f32_e32 v41, v36
	v_sub_u32_e32 v36, 0x80, v115
	v_cvt_f32_i32_e32 v36, v36
	v_mov_b32_e32 v45, v30
	v_mov_b32_e32 v43, v70
	v_mul_f32_e32 v36, v36, v130
	v_mul_f32_e32 v36, 0xbfb8aa3b, v36
	v_exp_f32_e32 v40, v36
	v_mov_b32_e32 v36, v6
	v_pk_mul_f32 v[36:37], v[40:41], v[36:37]
	s_nop 0
	v_add_f32_e32 v2, v37, v66
	v_pk_mul_f32 v[38:39], v[40:41], v[38:39]
	v_add_f32_e32 v36, v36, v2
	v_add_f32_e32 v2, v39, v78
	v_add_f32_e32 v46, v38, v2
	v_mov_b32_e32 v38, v22
	v_mov_b32_e32 v39, v18
	v_pk_mul_f32 v[38:39], v[40:41], v[38:39]
	v_mul_f32_e32 v42, v46, v46
	v_add_f32_e32 v2, v39, v74
	v_add_f32_e32 v38, v38, v2
	v_mov_b32_e32 v37, v41
	v_mov_b32_e32 v44, v36
	v_pk_fma_f32 v[42:43], v[36:37], v[44:45], v[42:43]
	v_mov_b32_e32 v39, v40
	v_mov_b32_e32 v40, v38
	v_mov_b32_e32 v41, v26
	v_pk_fma_f32 v[40:41], v[38:39], v[40:41], v[42:43]
	v_add_u32_e32 v42, s6, v115
	v_mad_i64_i32 v[44:45], s[0:1], v42, s3, v[98:99]
	v_lshl_add_u64 v[44:45], v[44:45], 0, s[26:27]
	v_lshl_add_u64 v[48:49], v[44:45], 0, v[0:1]
	v_lshl_add_u64 v[44:45], v[48:49], 0, s[10:11]
	v_add_co_u32_e32 v48, vcc, s7, v48
	v_ashrrev_i32_e32 v43, 31, v42
	s_nop 0
	v_addc_co_u32_e32 v49, vcc, 0, v49, vcc
	v_lshlrev_b64 v[42:43], 11, v[42:43]
	v_lshl_add_u64 v[42:43], s[4:5], 0, v[42:43]
	v_lshl_add_u64 v[42:43], v[42:43], 0, v[0:1]
	s_waitcnt vmcnt(16)
	v_lshlrev_b32_e32 v2, 16, v176
	v_mul_f32_e32 v6, 0xbfb8aa3b, v2
	v_exp_f32_e32 v6, v6
	s_nop 0
	v_add_f32_e32 v6, 1.0, v6
	v_div_scale_f32 v10, s[0:1], v6, v6, v2
	v_rcp_f32_e32 v14, v10
	s_nop 0
	v_fma_f32 v18, -v10, v14, 1.0
	v_fmac_f32_e32 v14, v18, v14
	v_div_scale_f32 v18, vcc, v2, v6, v2
	v_mul_f32_e32 v22, v18, v14
	v_fma_f32 v26, -v10, v22, v18
	v_fmac_f32_e32 v22, v26, v14
	v_fma_f32 v10, -v10, v22, v18
	v_div_fmas_f32 v10, v10, v14, v22
	v_div_fixup_f32 v22, v10, v6, v2
	s_nop 0
	v_lshlrev_b32_e32 v2, 16, v177
	v_mul_f32_e32 v6, 0xbfb8aa3b, v2
	v_exp_f32_e32 v6, v6
	s_nop 0
	v_add_f32_e32 v6, 1.0, v6
	v_div_scale_f32 v10, s[0:1], v6, v6, v2
	v_rcp_f32_e32 v14, v10
	s_nop 0
	v_fma_f32 v18, -v10, v14, 1.0
	v_fmac_f32_e32 v14, v18, v14
	v_div_scale_f32 v18, vcc, v2, v6, v2
	v_mul_f32_e32 v26, v18, v14
	v_fma_f32 v30, -v10, v26, v18
	v_fmac_f32_e32 v26, v30, v14
	v_fma_f32 v10, -v10, v26, v18
	v_div_fmas_f32 v10, v10, v14, v26
	v_div_fixup_f32 v37, v10, v6, v2
	s_nop 0
	v_lshlrev_b32_e32 v2, 16, v178
	v_mul_f32_e32 v6, 0xbfb8aa3b, v2
	v_exp_f32_e32 v6, v6
	s_nop 0
	v_add_f32_e32 v6, 1.0, v6
	v_div_scale_f32 v10, s[0:1], v6, v6, v2
	v_rcp_f32_e32 v14, v10
	s_nop 0
	v_fma_f32 v18, -v10, v14, 1.0
	v_fmac_f32_e32 v14, v18, v14
	v_div_scale_f32 v18, vcc, v2, v6, v2
	v_mul_f32_e32 v26, v18, v14
	v_fma_f32 v30, -v10, v26, v18
	v_fmac_f32_e32 v26, v30, v14
	v_fma_f32 v10, -v10, v26, v18
	v_div_fmas_f32 v10, v10, v14, v26
	v_div_fixup_f32 v39, v10, v6, v2
	s_nop 0
	v_lshlrev_b32_e32 v2, 16, v179
	v_mul_f32_e32 v6, 0xbfb8aa3b, v2
	v_exp_f32_e32 v6, v6
	s_nop 0
	v_add_f32_e32 v6, 1.0, v6
	v_div_scale_f32 v10, s[0:1], v6, v6, v2
	v_rcp_f32_e32 v14, v10
	s_nop 0
	v_fma_f32 v18, -v10, v14, 1.0
	v_fmac_f32_e32 v14, v18, v14
	v_div_scale_f32 v18, vcc, v2, v6, v2
	v_mul_f32_e32 v26, v18, v14
	v_fma_f32 v30, -v10, v26, v18
	v_fmac_f32_e32 v26, v30, v14
	v_fma_f32 v10, -v10, v26, v18
	v_div_fmas_f32 v10, v10, v14, v26
	v_div_fixup_f32 v47, v10, v6, v2
	v_cvt_f32_i32_e32 v2, v111
	v_mov_b32_e32 v10, v15
	v_mov_b32_e32 v18, v23
	v_mul_f32_e32 v2, v2, v131
	v_mul_f32_e32 v2, 0xbfb8aa3b, v2
	v_exp_f32_e32 v45, v2
	v_sub_u32_e32 v2, 0x80, v112
	v_cvt_f32_i32_e32 v2, v2
	v_mov_b32_e32 v15, v45
	v_mul_f32_e32 v2, v2, v130
	v_mul_f32_e32 v2, 0xbfb8aa3b, v2
	v_exp_f32_e32 v44, v2
	v_mov_b32_e32 v2, v7
	v_pk_mul_f32 v[2:3], v[44:45], v[2:3]
	s_nop 0
	v_add_f32_e32 v3, v3, v67
	v_add_f32_e32 v14, v2, v3
	v_pk_mul_f32 v[2:3], v[44:45], v[10:11]
	v_mov_b32_e32 v30, v14
	v_add_f32_e32 v3, v3, v79
	v_add_f32_e32 v48, v2, v3
	v_pk_mul_f32 v[2:3], v[44:45], v[18:19]
	v_mul_f32_e32 v70, v48, v48
	v_add_f32_e32 v3, v3, v75
	v_add_f32_e32 v6, v2, v3
	v_pk_fma_f32 v[2:3], v[14:15], v[30:31], v[70:71]
	v_mov_b32_e32 v7, v44
	v_mov_b32_e32 v26, v6
	v_pk_fma_f32 v[2:3], v[6:7], v[26:27], v[2:3]
	v_mov_b32_e32 v11, v41
	v_mov_b32_e32 v10, v3
	v_mov_b32_e32 v18, v2
	v_mov_b32_e32 v19, v40
	v_pk_fma_f32 v[10:11], v[10:11], v[10:11], v[18:19]
	s_nop 1
	v_add_f32_dpp v10, v10, v10 quad_perm:[1,0,3,2] row_mask:0xf bank_mask:0xf
	v_add_f32_dpp v11, v11, v11 quad_perm:[1,0,3,2] row_mask:0xf bank_mask:0xf
	s_nop 0
	v_add_f32_dpp v10, v10, v10 quad_perm:[2,3,0,1] row_mask:0xf bank_mask:0xf
	v_add_f32_dpp v11, v11, v11 quad_perm:[2,3,0,1] row_mask:0xf bank_mask:0xf
	s_nop 0
	v_add_f32_dpp v10, v10, v10 row_half_mirror row_mask:0xf bank_mask:0xf
	v_add_f32_dpp v11, v11, v11 row_half_mirror row_mask:0xf bank_mask:0xf
	s_nop 0
	v_add_f32_dpp v10, v10, v10 row_mirror row_mask:0xf bank_mask:0xf
	v_add_f32_dpp v11, v11, v11 row_mirror row_mask:0xf bank_mask:0xf
	s_nop 0
	s_nop 0
	v_pk_fma_f32 v[10:11], v[10:11], s[12:13], v[34:35] op_sel_hi:[1,0,0]
	s_nop 0
	v_mul_f32_e32 v2, 0x4b800000, v11
	v_cmp_gt_f32_e64 s[0:1], s8, v11
	v_cmp_gt_f32_e32 vcc, s8, v10
	s_nop 0
	v_cndmask_b32_e64 v2, v11, v2, s[0:1]
	v_rsq_f32_e32 v2, v2
	s_nop 0
	v_mul_f32_e32 v7, 0x45800000, v2
	v_cndmask_b32_e64 v2, v2, v7, s[0:1]
	v_mul_f32_e32 v7, v36, v2
	v_mul_f32_e32 v7, v22, v7
	v_cvt_pk_bf16_f32 v7, v7, s0
	global_store_short v[42:43], v7, off
	v_mul_f32_e32 v7, v46, v2
	v_mul_f32_e32 v7, v7, v37
	v_cvt_pk_bf16_f32 v7, v7, s0
	global_store_short v[42:43], v7, off offset:32
	v_mul_f32_e32 v7, v38, v2
	v_mul_f32_e32 v2, v41, v2
	v_mul_f32_e32 v2, v2, v47
	v_cvt_pk_bf16_f32 v2, v2, s0
	global_store_short v[42:43], v2, off offset:96
	v_mul_f32_e32 v2, 0x4b800000, v10
	v_cndmask_b32_e32 v2, v10, v2, vcc
	v_rsq_f32_e32 v2, v2
	v_mul_f32_e32 v7, v7, v39
	v_add_u32_e32 v10, s6, v112
	v_cvt_pk_bf16_f32 v7, v7, s0
	v_mad_i64_i32 v[18:19], s[0:1], v10, s3, v[98:99]
	v_ashrrev_i32_e32 v11, 31, v10
	v_lshl_add_u64 v[18:19], v[18:19], 0, s[26:27]
	global_store_short v[42:43], v7, off offset:64
	v_mul_f32_e32 v7, 0x45800000, v2
	v_lshlrev_b64 v[10:11], 11, v[10:11]
	v_lshl_add_u64 v[18:19], v[18:19], 0, v[0:1]
	v_cndmask_b32_e32 v2, v2, v7, vcc
	v_lshl_add_u64 v[22:23], s[4:5], 0, v[10:11]
	v_lshl_add_u64 v[10:11], v[18:19], 0, s[10:11]
	v_add_co_u32_e32 v18, vcc, s7, v18
	v_mul_f32_e32 v14, v14, v2
	s_nop 0
	v_addc_co_u32_e32 v19, vcc, 0, v19, vcc
	v_mul_f32_e32 v6, v6, v2
	s_nop 0
	v_lshlrev_b32_e32 v7, 16, v180
	v_mul_f32_e32 v15, 0xbfb8aa3b, v7
	v_exp_f32_e32 v15, v15
	s_nop 0
	v_add_f32_e32 v15, 1.0, v15
	v_div_scale_f32 v18, s[0:1], v15, v15, v7
	v_rcp_f32_e32 v19, v18
	s_nop 0
	v_fma_f32 v26, -v18, v19, 1.0
	v_fmac_f32_e32 v19, v26, v19
	v_div_scale_f32 v26, vcc, v7, v15, v7
	v_mul_f32_e32 v27, v26, v19
	v_fma_f32 v30, -v18, v27, v26
	v_fmac_f32_e32 v27, v30, v19
	v_fma_f32 v18, -v18, v27, v26
	v_div_fmas_f32 v18, v18, v19, v27
	v_div_fixup_f32 v7, v18, v15, v7
	v_mul_f32_e32 v7, v7, v14
	v_cvt_pk_bf16_f32 v7, v7, s0
	v_lshl_add_u64 v[14:15], v[22:23], 0, v[0:1]
	global_store_short v[14:15], v7, off
	v_mul_f32_e32 v18, v48, v2
	v_mul_f32_e32 v2, v3, v2
	s_nop 0
	v_lshlrev_b32_e32 v7, 16, v181
	v_mul_f32_e32 v19, 0xbfb8aa3b, v7
	v_exp_f32_e32 v19, v19
	s_nop 0
	v_add_f32_e32 v19, 1.0, v19
	v_div_scale_f32 v22, s[0:1], v19, v19, v7
	v_rcp_f32_e32 v23, v22
	s_nop 0
	v_fma_f32 v26, -v22, v23, 1.0
	v_fmac_f32_e32 v23, v26, v23
	v_div_scale_f32 v26, vcc, v7, v19, v7
	v_mul_f32_e32 v27, v26, v23
	v_fma_f32 v30, -v22, v27, v26
	v_fmac_f32_e32 v27, v30, v23
	v_fma_f32 v22, -v22, v27, v26
	v_div_fmas_f32 v22, v22, v23, v27
	v_div_fixup_f32 v7, v22, v19, v7
	v_mul_f32_e32 v7, v18, v7
	v_cvt_pk_bf16_f32 v7, v7, s0
	global_store_short v[14:15], v7, off offset:32
	s_nop 0
	v_lshlrev_b32_e32 v7, 16, v182
	v_mul_f32_e32 v18, 0xbfb8aa3b, v7
	v_exp_f32_e32 v18, v18
	s_nop 0
	v_add_f32_e32 v18, 1.0, v18
	v_div_scale_f32 v19, s[0:1], v18, v18, v7
	v_rcp_f32_e32 v22, v19
	s_nop 0
	v_fma_f32 v23, -v19, v22, 1.0
	v_fmac_f32_e32 v22, v23, v22
	v_div_scale_f32 v23, vcc, v7, v18, v7
	v_mul_f32_e32 v26, v23, v22
	v_fma_f32 v27, -v19, v26, v23
	v_fmac_f32_e32 v26, v27, v22
	v_fma_f32 v19, -v19, v26, v23
	v_div_fmas_f32 v19, v19, v22, v26
	v_div_fixup_f32 v7, v19, v18, v7
	v_mul_f32_e32 v6, v6, v7
	v_cvt_pk_bf16_f32 v6, v6, s0
	global_store_short v[14:15], v6, off offset:64
	s_nop 0
	v_lshlrev_b32_e32 v6, 16, v183
	v_mul_f32_e32 v3, 0xbfb8aa3b, v6
	v_exp_f32_e32 v3, v3
	s_nop 0
	v_add_f32_e32 v3, 1.0, v3
	v_div_scale_f32 v7, s[0:1], v3, v3, v6
	v_rcp_f32_e32 v10, v7
	s_nop 0
	v_fma_f32 v11, -v7, v10, 1.0
	v_fmac_f32_e32 v10, v11, v10
	v_div_scale_f32 v11, vcc, v6, v3, v6
	v_mul_f32_e32 v18, v11, v10
	v_fma_f32 v19, -v7, v18, v11
	v_fmac_f32_e32 v18, v19, v10
	v_fma_f32 v7, -v7, v18, v11
	v_div_fmas_f32 v7, v7, v10, v18
	v_div_fixup_f32 v3, v7, v3, v6
	v_mul_f32_e32 v2, v2, v3
	v_cvt_pk_bf16_f32 v2, v2, s0
	global_store_short v[14:15], v2, off offset:96
	v_cvt_f32_i32_e32 v2, v110
	v_mov_b32_e32 v3, v4
	v_mov_b32_e32 v6, v16
	v_mov_b32_e32 v7, v12
	v_mul_f32_e32 v2, v2, v131
	v_mul_f32_e32 v2, 0xbfb8aa3b, v2
	v_exp_f32_e32 v11, v2
	v_sub_u32_e32 v2, 0x80, v111
	v_cvt_f32_i32_e32 v2, v2
	v_mov_b32_e32 v19, v32
	v_mov_b32_e32 v15, v72
	v_mul_f32_e32 v2, v2, v130
	v_mul_f32_e32 v2, 0xbfb8aa3b, v2
	v_exp_f32_e32 v10, v2
	v_mov_b32_e32 v2, v8
	v_pk_mul_f32 v[2:3], v[10:11], v[2:3]
	s_nop 0
	v_add_f32_e32 v3, v3, v68
	v_pk_mul_f32 v[6:7], v[10:11], v[6:7]
	v_add_f32_e32 v2, v2, v3
	v_add_f32_e32 v3, v7, v80
	v_add_f32_e32 v22, v6, v3
	v_mov_b32_e32 v6, v24
	v_mov_b32_e32 v7, v20
	v_pk_mul_f32 v[6:7], v[10:11], v[6:7]
	v_mul_f32_e32 v14, v22, v22
	v_add_f32_e32 v3, v7, v76
	v_add_f32_e32 v6, v6, v3
	v_mov_b32_e32 v3, v11
	v_mov_b32_e32 v18, v2
	v_pk_fma_f32 v[14:15], v[2:3], v[18:19], v[14:15]
	v_mov_b32_e32 v7, v10
	v_mov_b32_e32 v10, v6
	v_mov_b32_e32 v11, v28
	v_pk_fma_f32 v[10:11], v[6:7], v[10:11], v[14:15]
	v_add_u32_e32 v14, s6, v111
	v_mad_i64_i32 v[18:19], s[0:1], v14, s3, v[98:99]
	v_lshl_add_u64 v[18:19], v[18:19], 0, s[26:27]
	v_lshl_add_u64 v[26:27], v[18:19], 0, v[0:1]
	v_lshl_add_u64 v[18:19], v[26:27], 0, s[10:11]
	v_add_co_u32_e32 v26, vcc, s7, v26
	v_ashrrev_i32_e32 v15, 31, v14
	s_nop 0
	v_addc_co_u32_e32 v27, vcc, 0, v27, vcc
	v_lshlrev_b64 v[14:15], 11, v[14:15]
	v_lshl_add_u64 v[14:15], s[4:5], 0, v[14:15]
	v_lshl_add_u64 v[14:15], v[14:15], 0, v[0:1]
	s_nop 0
	v_lshlrev_b32_e32 v3, 16, v184
	v_mul_f32_e32 v4, 0xbfb8aa3b, v3
	v_exp_f32_e32 v4, v4
	s_nop 0
	v_add_f32_e32 v4, 1.0, v4
	v_div_scale_f32 v7, s[0:1], v4, v4, v3
	v_rcp_f32_e32 v8, v7
	s_nop 0
	v_fma_f32 v12, -v7, v8, 1.0
	v_fmac_f32_e32 v8, v12, v8
	v_div_scale_f32 v12, vcc, v3, v4, v3
	v_mul_f32_e32 v16, v12, v8
	v_fma_f32 v20, -v7, v16, v12
	v_fmac_f32_e32 v16, v20, v8
	v_fma_f32 v7, -v7, v16, v12
	v_div_fmas_f32 v7, v7, v8, v16
	v_div_fixup_f32 v3, v7, v4, v3
	s_nop 0
	v_lshlrev_b32_e32 v4, 16, v185
	v_mul_f32_e32 v7, 0xbfb8aa3b, v4
	v_exp_f32_e32 v7, v7
	s_nop 0
	v_add_f32_e32 v7, 1.0, v7
	v_div_scale_f32 v8, s[0:1], v7, v7, v4
	v_rcp_f32_e32 v12, v8
	s_nop 0
	v_fma_f32 v16, -v8, v12, 1.0
	v_fmac_f32_e32 v12, v16, v12
	v_div_scale_f32 v16, vcc, v4, v7, v4
	v_mul_f32_e32 v20, v16, v12
	v_fma_f32 v23, -v8, v20, v16
	v_fmac_f32_e32 v20, v23, v12
	v_fma_f32 v8, -v8, v20, v16
	v_div_fmas_f32 v8, v8, v12, v20
	v_div_fixup_f32 v7, v8, v7, v4
	s_nop 0
	v_lshlrev_b32_e32 v4, 16, v186
	v_mul_f32_e32 v8, 0xbfb8aa3b, v4
	v_exp_f32_e32 v8, v8
	s_nop 0
	v_add_f32_e32 v8, 1.0, v8
	v_div_scale_f32 v12, s[0:1], v8, v8, v4
	v_rcp_f32_e32 v16, v12
	s_nop 0
	v_fma_f32 v20, -v12, v16, 1.0
	v_fmac_f32_e32 v16, v20, v16
	v_div_scale_f32 v20, vcc, v4, v8, v4
	v_mul_f32_e32 v23, v20, v16
	v_fma_f32 v24, -v12, v23, v20
	v_fmac_f32_e32 v23, v24, v16
	v_fma_f32 v12, -v12, v23, v20
	v_div_fmas_f32 v12, v12, v16, v23
	v_div_fixup_f32 v23, v12, v8, v4
	s_nop 0
	v_lshlrev_b32_e32 v4, 16, v187
	v_mul_f32_e32 v8, 0xbfb8aa3b, v4
	v_exp_f32_e32 v8, v8
	s_nop 0
	v_add_f32_e32 v8, 1.0, v8
	v_div_scale_f32 v12, s[0:1], v8, v8, v4
	v_rcp_f32_e32 v16, v12
	s_nop 0
	v_fma_f32 v18, -v12, v16, 1.0
	v_fmac_f32_e32 v16, v18, v16
	v_div_scale_f32 v18, vcc, v4, v8, v4
	v_mul_f32_e32 v19, v18, v16
	v_fma_f32 v20, -v12, v19, v18
	v_fmac_f32_e32 v19, v20, v16
	v_fma_f32 v12, -v12, v19, v18
	v_div_fmas_f32 v12, v12, v16, v19
	v_div_fixup_f32 v24, v12, v8, v4
	v_add_u32_e32 v4, 20, v132
	v_cvt_f32_i32_e32 v4, v4
	v_mov_b32_e32 v12, v17
	v_mov_b32_e32 v20, v25
	v_mul_f32_e32 v4, v4, v131
	v_mul_f32_e32 v4, 0xbfb8aa3b, v4
	v_exp_f32_e32 v19, v4
	v_sub_u32_e32 v4, 0x80, v110
	v_cvt_f32_i32_e32 v4, v4
	v_mov_b32_e32 v17, v19
	v_mul_f32_e32 v4, v4, v130
	v_mul_f32_e32 v4, 0xbfb8aa3b, v4
	v_exp_f32_e32 v18, v4
	v_mov_b32_e32 v4, v9
	v_pk_mul_f32 v[4:5], v[18:19], v[4:5]
	s_nop 0
	v_add_f32_e32 v5, v5, v69
	v_add_f32_e32 v16, v4, v5
	v_pk_mul_f32 v[4:5], v[18:19], v[12:13]
	v_mov_b32_e32 v32, v16
	v_add_f32_e32 v5, v5, v81
	v_add_f32_e32 v26, v4, v5
	v_pk_mul_f32 v[4:5], v[18:19], v[20:21]
	v_mul_f32_e32 v72, v26, v26
	v_add_f32_e32 v5, v5, v77
	v_add_f32_e32 v8, v4, v5
	v_pk_fma_f32 v[4:5], v[16:17], v[32:33], v[72:73]
	v_mov_b32_e32 v9, v18
	v_mov_b32_e32 v28, v8
	v_pk_fma_f32 v[4:5], v[8:9], v[28:29], v[4:5]
	v_mov_b32_e32 v13, v11
	v_mov_b32_e32 v12, v5
	v_mov_b32_e32 v18, v4
	v_mov_b32_e32 v19, v10
	v_pk_fma_f32 v[12:13], v[12:13], v[12:13], v[18:19]
	s_nop 1
	v_add_f32_dpp v12, v12, v12 quad_perm:[1,0,3,2] row_mask:0xf bank_mask:0xf
	v_add_f32_dpp v13, v13, v13 quad_perm:[1,0,3,2] row_mask:0xf bank_mask:0xf
	s_nop 0
	v_add_f32_dpp v12, v12, v12 quad_perm:[2,3,0,1] row_mask:0xf bank_mask:0xf
	v_add_f32_dpp v13, v13, v13 quad_perm:[2,3,0,1] row_mask:0xf bank_mask:0xf
	s_nop 0
	v_add_f32_dpp v12, v12, v12 row_half_mirror row_mask:0xf bank_mask:0xf
	v_add_f32_dpp v13, v13, v13 row_half_mirror row_mask:0xf bank_mask:0xf
	s_nop 0
	v_add_f32_dpp v12, v12, v12 row_mirror row_mask:0xf bank_mask:0xf
	v_add_f32_dpp v13, v13, v13 row_mirror row_mask:0xf bank_mask:0xf
	s_nop 0
	s_nop 0
	v_pk_fma_f32 v[12:13], v[12:13], s[12:13], v[34:35] op_sel_hi:[1,0,0]
	s_nop 0
	v_mul_f32_e32 v4, 0x4b800000, v13
	v_cmp_gt_f32_e64 s[0:1], s8, v13
	v_cmp_gt_f32_e32 vcc, s8, v12
	s_nop 0
	v_cndmask_b32_e64 v4, v13, v4, s[0:1]
	v_rsq_f32_e32 v4, v4
	s_nop 0
	v_mul_f32_e32 v9, 0x45800000, v4
	v_cndmask_b32_e64 v4, v4, v9, s[0:1]
	v_mul_f32_e32 v2, v2, v4
	v_mul_f32_e32 v2, v3, v2
	v_cvt_pk_bf16_f32 v2, v2, s0
	global_store_short v[14:15], v2, off
	v_mul_f32_e32 v2, v22, v4
	v_mul_f32_e32 v2, v2, v7
	v_cvt_pk_bf16_f32 v2, v2, s0
	global_store_short v[14:15], v2, off offset:32
	v_mul_f32_e32 v2, v6, v4
	v_mul_f32_e32 v2, v2, v23
	v_cvt_pk_bf16_f32 v2, v2, s0
	global_store_short v[14:15], v2, off offset:64
	v_mul_f32_e32 v2, v11, v4
	v_mul_f32_e32 v2, v2, v24
	v_cvt_pk_bf16_f32 v2, v2, s0
	global_store_short v[14:15], v2, off offset:96
	v_mul_f32_e32 v2, 0x4b800000, v12
	v_cndmask_b32_e32 v2, v12, v2, vcc
	v_rsq_f32_e32 v2, v2
	s_nop 0
	v_mul_f32_e32 v3, 0x45800000, v2
	v_cndmask_b32_e32 v4, v2, v3, vcc
	v_add_u32_e32 v2, s6, v110
	v_mad_i64_i32 v[6:7], s[0:1], v2, s3, v[98:99]
	v_lshl_add_u64 v[6:7], v[6:7], 0, s[26:27]
	v_lshl_add_u64 v[10:11], v[6:7], 0, v[0:1]
	v_lshl_add_u64 v[6:7], v[10:11], 0, s[10:11]
	v_add_co_u32_e32 v10, vcc, s7, v10
	v_ashrrev_i32_e32 v3, 31, v2
	s_nop 0
	v_addc_co_u32_e32 v11, vcc, 0, v11, vcc
	v_lshlrev_b64 v[2:3], 11, v[2:3]
	v_lshl_add_u64 v[2:3], s[4:5], 0, v[2:3]
	v_lshl_add_u64 v[2:3], v[2:3], 0, v[0:1]
	v_mul_f32_e32 v10, v16, v4
	v_mul_f32_e32 v8, v8, v4
	s_nop 0
	v_lshlrev_b32_e32 v9, 16, v188
	v_mul_f32_e32 v11, 0xbfb8aa3b, v9
	v_exp_f32_e32 v11, v11
	s_nop 0
	v_lshlrev_b32_e32 v0, 16, v189
	v_add_f32_e32 v11, 1.0, v11
	v_div_scale_f32 v12, s[0:1], v11, v11, v9
	v_rcp_f32_e32 v13, v12
	s_nop 0
	v_fma_f32 v14, -v12, v13, 1.0
	v_fmac_f32_e32 v13, v14, v13
	v_div_scale_f32 v14, vcc, v9, v11, v9
	v_mul_f32_e32 v15, v14, v13
	v_fma_f32 v16, -v12, v15, v14
	v_fmac_f32_e32 v15, v16, v13
	v_fma_f32 v12, -v12, v15, v14
	v_div_fmas_f32 v12, v12, v13, v15
	v_div_fixup_f32 v9, v12, v11, v9
	v_mul_f32_e32 v9, v9, v10
	v_mul_f32_e32 v10, 0xbfb8aa3b, v0
	v_exp_f32_e32 v10, v10
	v_cvt_pk_bf16_f32 v9, v9, s0
	global_store_short v[2:3], v9, off
	v_mul_f32_e32 v9, v26, v4
	v_add_f32_e32 v10, 1.0, v10
	v_div_scale_f32 v11, s[0:1], v10, v10, v0
	v_rcp_f32_e32 v12, v11
	v_mul_f32_e32 v4, v5, v4
	v_fma_f32 v13, -v11, v12, 1.0
	v_fmac_f32_e32 v12, v13, v12
	v_div_scale_f32 v13, vcc, v0, v10, v0
	v_mul_f32_e32 v14, v13, v12
	v_fma_f32 v15, -v11, v14, v13
	v_fmac_f32_e32 v14, v15, v12
	v_fma_f32 v11, -v11, v14, v13
	v_div_fmas_f32 v11, v11, v12, v14
	v_div_fixup_f32 v0, v11, v10, v0
	v_mul_f32_e32 v0, v9, v0
	v_cvt_pk_bf16_f32 v0, v0, s0
	global_store_short v[2:3], v0, off offset:32
	s_nop 0
	v_lshlrev_b32_e32 v0, 16, v190
	v_mul_f32_e32 v9, 0xbfb8aa3b, v0
	v_exp_f32_e32 v9, v9
	s_nop 0
	v_add_f32_e32 v9, 1.0, v9
	v_div_scale_f32 v10, s[0:1], v9, v9, v0
	v_rcp_f32_e32 v11, v10
	s_nop 0
	v_fma_f32 v12, -v10, v11, 1.0
	v_fmac_f32_e32 v11, v12, v11
	v_div_scale_f32 v12, vcc, v0, v9, v0
	v_mul_f32_e32 v13, v12, v11
	v_fma_f32 v14, -v10, v13, v12
	v_fmac_f32_e32 v13, v14, v11
	v_fma_f32 v10, -v10, v13, v12
	v_div_fmas_f32 v10, v10, v11, v13
	v_div_fixup_f32 v0, v10, v9, v0
	v_mul_f32_e32 v0, v8, v0
	v_cvt_pk_bf16_f32 v0, v0, s0
	global_store_short v[2:3], v0, off offset:64
	s_nop 0
	v_lshlrev_b32_e32 v0, 16, v191
	v_mul_f32_e32 v5, 0xbfb8aa3b, v0
	v_exp_f32_e32 v5, v5
	s_nop 0
	v_add_f32_e32 v5, 1.0, v5
	v_div_scale_f32 v6, s[0:1], v5, v5, v0
	v_rcp_f32_e32 v7, v6
	s_nop 0
	v_fma_f32 v8, -v6, v7, 1.0
	v_fmac_f32_e32 v7, v8, v7
	v_div_scale_f32 v8, vcc, v0, v5, v0
	v_mul_f32_e32 v9, v8, v7
	v_fma_f32 v10, -v6, v9, v8
	v_fmac_f32_e32 v9, v10, v7
	v_fma_f32 v6, -v6, v9, v8
	v_div_fmas_f32 v6, v6, v7, v9
	v_div_fixup_f32 v0, v6, v5, v0
	v_mul_f32_e32 v0, v4, v0
	v_cvt_pk_bf16_f32 v0, v0, s0
	global_store_short v[2:3], v0, off offset:96
	s_barrier
	s_branch .LBB0_184
